# P1 gla q/k epilogue: decay loads prefetched in two batches of 16 instead of 32 serialized round trips
# baseline (speedup 1.0000x reference)
; DEV u32x2 pk4(f32x4 v) { u32x2 r = {pk_bf16(v[0], v[1]), pk_bf16(v[2], v[3])}; return r; }
; DEV int sig4(int x) { return ((x & 1) << 1) | (x >> 1); }
; DEV float fsigmoid(float x) { return 1.f / (1.f + __expf(-x)); }
;   DEV void operator()(f32x4 (&acc)[2][2][4][2], int brow, int bcol, int wr, int wc, int fr, int fq) const {
;     ...
;       for (int m = 0; m < 4; ++m) {
;         const int rl = ai * 128 + wr * 64 + m * 16 + fr, tok = brow + rl;
; #pragma unroll
;         for (int bj = 0; bj < 2; ++bj)
; #pragma unroll
;           for (int n = 0; n < 2; ++n) {
;             const int cl = bj * 128 + wc * 32 + n * 16 + fq * 4, lc = bcol - segstart + cl;
;             f32x4 v = acc[ai][bj][m][n];
;             if (mode == 0) {
;               tile_put4(rl, cl, pk4(v * scale));
;             } else if (mode == 1) {
;               for (int j = 0; j < 4; ++j) v[j] = v[j] * fsigmoid(v[j]);
;               tile_put4(rl, cl, pk4(v));
;             } else if (mode == 2) {
;               for (int j = 0; j < 4; ++j) v[j] = fsigmoid(v[j]);
;               tile_put4(rl, cl, pk4(v));
;             } else {
;               const f32x4 b4 = *(const f32x4*)(bmat + (size_t)tok * 1024 + lc);
;               const int pcl = (cl & ~15) + 4 * sig4((cl >> 2) & 3);
;               if (mode == 3) {
;                 for (int j = 0; j < 4; ++j) v[j] = v[j] * scale * __expf(b4[j]);
;                 tile_put4(rl, pcl, pk4(v));
;               } else {
;                 const f32x4 bl = *(const f32x4*)(bmat + (size_t)(tok | 63) * 1024 + lc);
;                 f32x4 kd, ke;
;                 for (int j = 0; j < 4; ++j) { kd[j] = v[j] * __expf(-b4[j]); ke[j] = v[j] * __expf(bl[j] - b4[j]); }
;                 tile_put4(rl, pcl, pk4(kd));
.LBB0_1580:
	s_or_b64 exec, exec, s[18:19]
	s_cmp_lt_i32 s37, 3
	s_cbranch_scc1 .Lp1_nopf
	v_readlane_b32 s20, v253, 54
	v_readlane_b32 s21, v253, 55
	v_ashrrev_i32_e32 v175, 2, v198
	v_and_b32_e32 v174, 15, v198
	v_and_b32_e32 v175, 0xffffffc0, v175
	v_or_b32_e32 v175, v175, v174
	v_add_u32_e32 v175, s4, v175
	v_lshlrev_b32_e32 v175, 12, v175
	v_bfe_u32 v174, v198, 6, 2
	v_lshlrev_b32_e32 v174, 5, v174
	v_add_u32_e32 v174, s6, v174
	v_subrev_u32_e32 v174, s36, v174
	v_lshl_add_u32 v175, v174, 2, v175
	v_bfe_u32 v174, v198, 4, 2
	v_lshl_add_u32 v175, v174, 4, v175
	global_load_dwordx4 v[180:183], v175, s[20:21]
	global_load_dwordx4 v[184:187], v175, s[20:21] offset:64
	global_load_dwordx4 v[188:191], v175, s[20:21] offset:512
	global_load_dwordx4 v[192:195], v175, s[20:21] offset:576
	v_add_u32_e32 v175, 0x10000, v175
	global_load_dwordx4 v[206:209], v175, s[20:21]
	global_load_dwordx4 v[210:213], v175, s[20:21] offset:64
	global_load_dwordx4 v[214:217], v175, s[20:21] offset:512
	global_load_dwordx4 v[224:227], v175, s[20:21] offset:576
	v_add_u32_e32 v175, 0x10000, v175
	global_load_dwordx4 v[228:231], v175, s[20:21]
	global_load_dwordx4 v[232:235], v175, s[20:21] offset:64
	global_load_dwordx4 v[236:239], v175, s[20:21] offset:512
	global_load_dwordx4 v[240:243], v175, s[20:21] offset:576
	v_add_u32_e32 v175, 0x10000, v175
	global_load_dwordx4 v[244:247], v175, s[20:21]
	global_load_dwordx4 v[248:251], v175, s[20:21] offset:64
	global_load_dwordx4 v[166:169], v175, s[20:21] offset:512
	global_load_dwordx4 v[170:173], v175, s[20:21] offset:576
	v_add_u32_e32 v175, 0x10000, v175
.Lp1_nopf:
	s_mov_b32 s5, s4
	s_mov_b32 s7, s6
	s_mov_b32 s18, s12
	v_ashrrev_i32_e32 v128, 2, v198
	v_and_b32_e32 v201, 15, v198
	v_and_b32_e32 v202, 0xffffffc0, v128
	v_lshrrev_b32_e32 v137, 4, v198
	v_or_b32_e32 v144, v202, v201
	v_bfe_u32 v138, v198, 6, 2
	v_bfe_u32 v139, v198, 4, 2
	v_lshrrev_b32_e32 v128, 3, v198
	v_bfe_u32 v140, v137, 1, 1
	v_add_u32_e32 v132, s5, v144
	v_lshlrev_b32_e32 v142, 5, v138
	v_lshlrev_b32_e32 v200, 2, v139
	v_and_or_b32 v128, v128, 2, v140
	v_ashrrev_i32_e32 v133, 31, v132
	v_lshlrev_b32_e32 v141, 2, v128
	v_lshl_add_u32 v136, v144, 9, 0
	v_lshlrev_b64 v[134:135], 12, v[132:133]
	v_or_b32_e32 v203, v142, v200
	s_mov_b32 s19, s12
	s_cmp_lt_i32 s37, 1
	s_mov_b64 s[20:21], -1
	s_cbranch_scc1 .LBB0_1594
	s_cmp_lt_i32 s37, 2
	s_cbranch_scc1 .LBB0_1591
	s_cmp_lg_u32 s37, 2
	s_cbranch_scc0 .LBB0_1588
	v_add_u32_e32 v128, s7, v203
	v_readlane_b32 s20, v253, 54
	v_subrev_u32_e32 v128, s36, v128
	v_readlane_b32 s21, v253, 55
	v_ashrrev_i32_e32 v129, 31, v128
	v_or_b32_e32 v133, v141, v142
	v_lshl_add_u64 v[130:131], s[20:21], 0, v[134:135]
	v_lshl_add_u64 v[128:129], v[128:129], 2, v[130:131]
	s_waitcnt vmcnt(0)
	v_mov_b32_e32 v128, v180
	v_mov_b32_e32 v129, v181
	v_mov_b32_e32 v130, v182
	v_mov_b32_e32 v131, v183
	v_lshrrev_b32_e32 v133, 3, v133
	s_mov_b64 s[20:21], -1
	s_and_b64 vcc, exec, s[16:17]
	v_xor_b32_e32 v133, v133, v201
	s_cbranch_vccz .LBB0_1585
	s_waitcnt vmcnt(0)
	v_mul_f32_e32 v143, 0xbfb8aa3b, v128
	v_exp_f32_e32 v146, v143
	v_mul_f32_e32 v143, 0xbfb8aa3b, v129
	v_exp_f32_e32 v147, v143
	v_mul_f32_e32 v143, 0xbfb8aa3b, v130
	v_exp_f32_e32 v148, v143
	v_mul_f32_e32 v143, 0xbfb8aa3b, v131
	v_exp_f32_e32 v149, v143
	v_pk_mul_f32 v[146:147], v[124:125], v[146:147]
	v_lshlrev_b32_e32 v143, 4, v133
	v_lshlrev_b32_e32 v145, 3, v140
	v_pk_mul_f32 v[148:149], v[126:127], v[148:149]
	v_cvt_pk_bf16_f32 v146, v146, v147
	v_cvt_pk_bf16_f32 v147, v148, v149
	v_add3_u32 v143, v136, v143, v145
	ds_write_b64 v143, v[146:147]
	s_mov_b64 s[20:21], 0

; DEV u32x2 pk4(f32x4 v) { u32x2 r = {pk_bf16(v[0], v[1]), pk_bf16(v[2], v[3])}; return r; }
; DEV int sig4(int x) { return ((x & 1) << 1) | (x >> 1); }
;   DEV void operator()(f32x4 (&acc)[2][2][4][2], int brow, int bcol, int wr, int wc, int fr, int fq) const {
;     ...
;               const f32x4 b4 = *(const f32x4*)(bmat + (size_t)tok * 1024 + lc);
;               const int pcl = (cl & ~15) + 4 * sig4((cl >> 2) & 3);
;               if (mode == 3) {
;                 for (int j = 0; j < 4; ++j) v[j] = v[j] * scale * __expf(b4[j]);
;                 tile_put4(rl, pcl, pk4(v));
;               } else {
;                 const f32x4 bl = *(const f32x4*)(bmat + (size_t)(tok | 63) * 1024 + lc);
;                 f32x4 kd, ke;
;                 for (int j = 0; j < 4; ++j) { kd[j] = v[j] * __expf(-b4[j]); ke[j] = v[j] * __expf(bl[j] - b4[j]); }
;                 tile_put4(rl, pcl, pk4(kd));
.LBB0_1596:
	v_or_b32_e32 v143, 16, v142
	v_or_b32_e32 v146, v143, v200
	s_cmp_lt_i32 s37, 1
	s_mov_b64 s[20:21], -1
	s_cbranch_scc1 .LBB0_1610
	s_cmp_lt_i32 s37, 2
	s_cbranch_scc1 .LBB0_1607
	s_cmp_lg_u32 s37, 2
	s_cbranch_scc0 .LBB0_1604
	s_sub_i32 s20, s7, s36
	v_add_u32_e32 v128, s20, v146
	v_readlane_b32 s20, v253, 54
	v_readlane_b32 s21, v253, 55
	v_ashrrev_i32_e32 v129, 31, v128
	v_or_b32_e32 v137, v141, v143
	v_lshl_add_u64 v[130:131], s[20:21], 0, v[134:135]
	v_lshl_add_u64 v[128:129], v[128:129], 2, v[130:131]
	s_waitcnt vmcnt(0)
	v_mov_b32_e32 v128, v184
	v_mov_b32_e32 v129, v185
	v_mov_b32_e32 v130, v186
	v_mov_b32_e32 v131, v187
	v_lshrrev_b32_e32 v137, 3, v137
	s_mov_b64 s[20:21], -1
	s_andn2_b64 vcc, exec, s[16:17]
	v_xor_b32_e32 v137, v137, v201
	s_cbranch_vccnz .LBB0_1601
	s_waitcnt vmcnt(0)
	v_mul_f32_e32 v145, 0xbfb8aa3b, v128
	v_exp_f32_e32 v148, v145
	v_mul_f32_e32 v145, 0xbfb8aa3b, v129
	v_exp_f32_e32 v149, v145
	v_mul_f32_e32 v145, 0xbfb8aa3b, v130
	v_exp_f32_e32 v152, v145
	v_mul_f32_e32 v145, 0xbfb8aa3b, v131
	v_exp_f32_e32 v153, v145
	v_pk_mul_f32 v[148:149], v[120:121], v[148:149]
	v_lshlrev_b32_e32 v145, 4, v137
	v_lshlrev_b32_e32 v147, 3, v140
	v_pk_mul_f32 v[152:153], v[122:123], v[152:153]
	v_cvt_pk_bf16_f32 v148, v148, v149
	v_cvt_pk_bf16_f32 v149, v152, v153
	v_add3_u32 v145, v136, v145, v147
	s_mov_b64 s[20:21], 0
	ds_write_b64 v145, v[148:149]

; DEV u32x2 pk4(f32x4 v) { u32x2 r = {pk_bf16(v[0], v[1]), pk_bf16(v[2], v[3])}; return r; }
; DEV int sig4(int x) { return ((x & 1) << 1) | (x >> 1); }
;   DEV void operator()(f32x4 (&acc)[2][2][4][2], int brow, int bcol, int wr, int wc, int fr, int fq) const {
;     ...
;               const f32x4 b4 = *(const f32x4*)(bmat + (size_t)tok * 1024 + lc);
;               const int pcl = (cl & ~15) + 4 * sig4((cl >> 2) & 3);
;               if (mode == 3) {
;                 for (int j = 0; j < 4; ++j) v[j] = v[j] * scale * __expf(b4[j]);
;                 tile_put4(rl, pcl, pk4(v));
;               } else {
;                 const f32x4 bl = *(const f32x4*)(bmat + (size_t)(tok | 63) * 1024 + lc);
;                 f32x4 kd, ke;
;                 for (int j = 0; j < 4; ++j) { kd[j] = v[j] * __expf(-b4[j]); ke[j] = v[j] * __expf(bl[j] - b4[j]); }
;                 tile_put4(rl, pcl, pk4(kd));
.LBB0_1612:
	v_or_b32_e32 v145, 0x80, v142
	v_or_b32_e32 v148, v145, v200
	s_cmp_lt_i32 s37, 1
	s_mov_b64 s[20:21], -1
	s_cbranch_scc1 .LBB0_1626
	s_cmp_lt_i32 s37, 2
	s_cbranch_scc1 .LBB0_1623
	s_cmp_lg_u32 s37, 2
	s_cbranch_scc0 .LBB0_1620
	s_sub_i32 s20, s7, s36
	s_waitcnt vmcnt(0)
	v_add_u32_e32 v128, s20, v148
	v_readlane_b32 s20, v253, 54
	v_readlane_b32 s21, v253, 55
	v_ashrrev_i32_e32 v129, 31, v128
	v_or_b32_e32 v137, v141, v145
	v_lshl_add_u64 v[130:131], s[20:21], 0, v[134:135]
	v_lshl_add_u64 v[128:129], v[128:129], 2, v[130:131]
	s_waitcnt vmcnt(0)
	v_mov_b32_e32 v128, v188
	v_mov_b32_e32 v129, v189
	v_mov_b32_e32 v130, v190
	v_mov_b32_e32 v131, v191
	v_lshrrev_b32_e32 v137, 3, v137
	s_mov_b64 s[20:21], -1
	s_andn2_b64 vcc, exec, s[16:17]
	v_xor_b32_e32 v137, v137, v201
	s_cbranch_vccnz .LBB0_1617
	s_waitcnt vmcnt(0)
	v_mul_f32_e32 v147, 0xbfb8aa3b, v128
	v_exp_f32_e32 v158, v147
	v_mul_f32_e32 v147, 0xbfb8aa3b, v129
	v_exp_f32_e32 v159, v147
	v_mul_f32_e32 v147, 0xbfb8aa3b, v130
	v_exp_f32_e32 v160, v147
	v_mul_f32_e32 v147, 0xbfb8aa3b, v131
	v_exp_f32_e32 v161, v147
	v_pk_mul_f32 v[158:159], v[116:117], v[158:159]
	v_lshlrev_b32_e32 v147, 4, v137
	v_lshlrev_b32_e32 v149, 3, v140
	v_pk_mul_f32 v[160:161], v[118:119], v[160:161]
	v_cvt_pk_bf16_f32 v158, v158, v159
	v_cvt_pk_bf16_f32 v159, v160, v161
	v_add3_u32 v147, v136, v147, v149
	s_mov_b64 s[20:21], 0
	ds_write_b64 v147, v[158:159]

; DEV u32x2 pk4(f32x4 v) { u32x2 r = {pk_bf16(v[0], v[1]), pk_bf16(v[2], v[3])}; return r; }
; DEV int sig4(int x) { return ((x & 1) << 1) | (x >> 1); }
;   DEV void operator()(f32x4 (&acc)[2][2][4][2], int brow, int bcol, int wr, int wc, int fr, int fq) const {
;     ...
;               const f32x4 b4 = *(const f32x4*)(bmat + (size_t)tok * 1024 + lc);
;               const int pcl = (cl & ~15) + 4 * sig4((cl >> 2) & 3);
;               if (mode == 3) {
;                 for (int j = 0; j < 4; ++j) v[j] = v[j] * scale * __expf(b4[j]);
;                 tile_put4(rl, pcl, pk4(v));
;               } else {
;                 const f32x4 bl = *(const f32x4*)(bmat + (size_t)(tok | 63) * 1024 + lc);
;                 f32x4 kd, ke;
;                 for (int j = 0; j < 4; ++j) { kd[j] = v[j] * __expf(-b4[j]); ke[j] = v[j] * __expf(bl[j] - b4[j]); }
;                 tile_put4(rl, pcl, pk4(kd));
.LBB0_1628:
	v_or_b32_e32 v147, 0x90, v142
	v_or_b32_e32 v149, v147, v200
	s_cmp_lt_i32 s37, 1
	s_mov_b64 s[20:21], -1
	s_cbranch_scc1 .LBB0_1642
	s_cmp_lt_i32 s37, 2
	s_cbranch_scc1 .LBB0_1639
	s_cmp_lg_u32 s37, 2
	s_cbranch_scc0 .LBB0_1636
	s_sub_i32 s20, s7, s36
	s_waitcnt vmcnt(0)
	v_add_u32_e32 v128, s20, v149
	v_readlane_b32 s20, v253, 54
	v_readlane_b32 s21, v253, 55
	v_ashrrev_i32_e32 v129, 31, v128
	v_or_b32_e32 v137, v141, v147
	v_lshl_add_u64 v[130:131], s[20:21], 0, v[134:135]
	v_lshl_add_u64 v[128:129], v[128:129], 2, v[130:131]
	s_waitcnt vmcnt(0)
	v_mov_b32_e32 v128, v192
	v_mov_b32_e32 v129, v193
	v_mov_b32_e32 v130, v194
	v_mov_b32_e32 v131, v195
	v_lshrrev_b32_e32 v137, 3, v137
	s_mov_b64 s[20:21], -1
	s_andn2_b64 vcc, exec, s[16:17]
	v_xor_b32_e32 v137, v137, v201
	s_cbranch_vccnz .LBB0_1633
	s_waitcnt vmcnt(0)
	v_mul_f32_e32 v150, 0xbfb8aa3b, v128
	v_exp_f32_e32 v158, v150
	v_mul_f32_e32 v150, 0xbfb8aa3b, v129
	v_exp_f32_e32 v159, v150
	v_mul_f32_e32 v150, 0xbfb8aa3b, v130
	v_exp_f32_e32 v160, v150
	v_mul_f32_e32 v150, 0xbfb8aa3b, v131
	v_exp_f32_e32 v161, v150
	v_pk_mul_f32 v[158:159], v[112:113], v[158:159]
	v_lshlrev_b32_e32 v150, 4, v137
	v_lshlrev_b32_e32 v154, 3, v140
	v_pk_mul_f32 v[160:161], v[114:115], v[160:161]
	v_cvt_pk_bf16_f32 v158, v158, v159
	v_cvt_pk_bf16_f32 v159, v160, v161
	v_add3_u32 v150, v136, v150, v154
	s_mov_b64 s[20:21], 0
	ds_write_b64 v150, v[158:159]

; DEV u32x2 pk4(f32x4 v) { u32x2 r = {pk_bf16(v[0], v[1]), pk_bf16(v[2], v[3])}; return r; }
; DEV int sig4(int x) { return ((x & 1) << 1) | (x >> 1); }
;   DEV void operator()(f32x4 (&acc)[2][2][4][2], int brow, int bcol, int wr, int wc, int fr, int fq) const {
;     ...
;               const f32x4 b4 = *(const f32x4*)(bmat + (size_t)tok * 1024 + lc);
;               const int pcl = (cl & ~15) + 4 * sig4((cl >> 2) & 3);
;               if (mode == 3) {
;                 for (int j = 0; j < 4; ++j) v[j] = v[j] * scale * __expf(b4[j]);
;                 tile_put4(rl, pcl, pk4(v));
;               } else {
;                 const f32x4 bl = *(const f32x4*)(bmat + (size_t)(tok | 63) * 1024 + lc);
;                 f32x4 kd, ke;
;                 for (int j = 0; j < 4; ++j) { kd[j] = v[j] * __expf(-b4[j]); ke[j] = v[j] * __expf(bl[j] - b4[j]); }
;                 tile_put4(rl, pcl, pk4(kd));
.LBB0_1644:
	s_waitcnt vmcnt(0)
	v_or_b32_e32 v129, 16, v144
	v_add_u32_e32 v128, s5, v129
	v_lshl_add_u32 v159, v129, 9, 0
	v_ashrrev_i32_e32 v129, 31, v128
	v_lshlrev_b64 v[136:137], 12, v[128:129]
	v_or_b32_e32 v150, 16, v201
	s_cmp_lt_i32 s37, 1
	s_mov_b64 s[20:21], -1
	s_cbranch_scc1 .LBB0_1700
	s_cmp_lt_i32 s37, 2
	s_cbranch_scc1 .LBB0_1655
	s_cmp_lg_u32 s37, 2
	s_cbranch_scc0 .LBB0_1652
	v_add_u32_e32 v128, s7, v203
	v_readlane_b32 s20, v253, 54
	v_subrev_u32_e32 v128, s36, v128
	v_readlane_b32 s21, v253, 55
	v_ashrrev_i32_e32 v129, 31, v128
	v_or_b32_e32 v160, v141, v142
	v_lshl_add_u64 v[130:131], s[20:21], 0, v[136:137]
	v_lshl_add_u64 v[128:129], v[128:129], 2, v[130:131]
	s_waitcnt vmcnt(0)
	v_mov_b32_e32 v128, v206
	v_mov_b32_e32 v129, v207
	v_mov_b32_e32 v130, v208
	v_mov_b32_e32 v131, v209
	v_lshrrev_b32_e32 v160, 3, v160
	s_mov_b64 s[20:21], -1
	s_andn2_b64 vcc, exec, s[16:17]
	v_xor_b32_e32 v160, v160, v150
	s_cbranch_vccnz .LBB0_1649
	s_waitcnt vmcnt(0)
	v_mul_f32_e32 v161, 0xbfb8aa3b, v128
	v_exp_f32_e32 v162, v161
	v_mul_f32_e32 v161, 0xbfb8aa3b, v129
	v_exp_f32_e32 v163, v161
	v_mul_f32_e32 v161, 0xbfb8aa3b, v130
	v_exp_f32_e32 v164, v161
	v_mul_f32_e32 v161, 0xbfb8aa3b, v131
	v_exp_f32_e32 v165, v161
	v_pk_mul_f32 v[162:163], v[108:109], v[162:163]
	v_lshlrev_b32_e32 v161, 4, v160
	v_cvt_pk_bf16_f32 v162, v162, v163
	v_pk_mul_f32 v[164:165], v[110:111], v[164:165]
	s_mov_b64 s[20:21], 0
	v_cvt_pk_bf16_f32 v163, v164, v165
	v_lshlrev_b32_e32 v164, 3, v140
	v_add3_u32 v161, v159, v161, v164
	ds_write_b64 v161, v[162:163]

; DEV u32x2 pk4(f32x4 v) { u32x2 r = {pk_bf16(v[0], v[1]), pk_bf16(v[2], v[3])}; return r; }
; DEV int sig4(int x) { return ((x & 1) << 1) | (x >> 1); }
;   DEV void operator()(f32x4 (&acc)[2][2][4][2], int brow, int bcol, int wr, int wc, int fr, int fq) const {
;     ...
;               const f32x4 b4 = *(const f32x4*)(bmat + (size_t)tok * 1024 + lc);
;               const int pcl = (cl & ~15) + 4 * sig4((cl >> 2) & 3);
;               if (mode == 3) {
;                 for (int j = 0; j < 4; ++j) v[j] = v[j] * scale * __expf(b4[j]);
;                 tile_put4(rl, pcl, pk4(v));
;               } else {
;                 const f32x4 bl = *(const f32x4*)(bmat + (size_t)(tok | 63) * 1024 + lc);
;                 f32x4 kd, ke;
;                 for (int j = 0; j < 4; ++j) { kd[j] = v[j] * __expf(-b4[j]); ke[j] = v[j] * __expf(bl[j] - b4[j]); }
;                 tile_put4(rl, pcl, pk4(kd));
.LBB0_1659:
	s_cmp_lt_i32 s37, 2
	s_cbranch_scc1 .LBB0_1669
	s_cmp_lg_u32 s37, 2
	s_cbranch_scc0 .LBB0_1666
	s_sub_i32 s20, s7, s36
	s_waitcnt vmcnt(0)
	v_add_u32_e32 v128, s20, v146
	v_readlane_b32 s20, v253, 54
	v_readlane_b32 s21, v253, 55
	v_ashrrev_i32_e32 v129, 31, v128
	v_or_b32_e32 v160, v141, v143
	v_lshl_add_u64 v[130:131], s[20:21], 0, v[136:137]
	v_lshl_add_u64 v[128:129], v[128:129], 2, v[130:131]
	s_waitcnt vmcnt(0)
	v_mov_b32_e32 v128, v210
	v_mov_b32_e32 v129, v211
	v_mov_b32_e32 v130, v212
	v_mov_b32_e32 v131, v213
	v_lshrrev_b32_e32 v160, 3, v160
	s_mov_b64 s[20:21], -1
	s_andn2_b64 vcc, exec, s[16:17]
	v_xor_b32_e32 v160, v160, v150
	s_cbranch_vccnz .LBB0_1663
	s_waitcnt vmcnt(0)
	v_mul_f32_e32 v161, 0xbfb8aa3b, v128
	v_exp_f32_e32 v162, v161
	v_mul_f32_e32 v161, 0xbfb8aa3b, v129
	v_exp_f32_e32 v163, v161
	v_mul_f32_e32 v161, 0xbfb8aa3b, v130
	v_exp_f32_e32 v164, v161
	v_mul_f32_e32 v161, 0xbfb8aa3b, v131
	v_exp_f32_e32 v165, v161
	v_pk_mul_f32 v[162:163], v[104:105], v[162:163]
	v_lshlrev_b32_e32 v161, 4, v160
	v_cvt_pk_bf16_f32 v162, v162, v163
	v_pk_mul_f32 v[164:165], v[106:107], v[164:165]
	s_mov_b64 s[20:21], 0
	v_cvt_pk_bf16_f32 v163, v164, v165
	v_lshlrev_b32_e32 v164, 3, v140
	v_add3_u32 v161, v159, v161, v164
	ds_write_b64 v161, v[162:163]

; DEV u32x2 pk4(f32x4 v) { u32x2 r = {pk_bf16(v[0], v[1]), pk_bf16(v[2], v[3])}; return r; }
; DEV int sig4(int x) { return ((x & 1) << 1) | (x >> 1); }
;   DEV void operator()(f32x4 (&acc)[2][2][4][2], int brow, int bcol, int wr, int wc, int fr, int fq) const {
;     ...
;               const f32x4 b4 = *(const f32x4*)(bmat + (size_t)tok * 1024 + lc);
;               const int pcl = (cl & ~15) + 4 * sig4((cl >> 2) & 3);
;               if (mode == 3) {
;                 for (int j = 0; j < 4; ++j) v[j] = v[j] * scale * __expf(b4[j]);
;                 tile_put4(rl, pcl, pk4(v));
;               } else {
;                 const f32x4 bl = *(const f32x4*)(bmat + (size_t)(tok | 63) * 1024 + lc);
;                 f32x4 kd, ke;
;                 for (int j = 0; j < 4; ++j) { kd[j] = v[j] * __expf(-b4[j]); ke[j] = v[j] * __expf(bl[j] - b4[j]); }
;                 tile_put4(rl, pcl, pk4(kd));
.LBB0_1673:
	s_cmp_lt_i32 s37, 2
	s_cbranch_scc1 .LBB0_1683
	s_cmp_lg_u32 s37, 2
	s_cbranch_scc0 .LBB0_1680
	s_sub_i32 s20, s7, s36
	s_waitcnt vmcnt(0)
	v_add_u32_e32 v128, s20, v148
	v_readlane_b32 s20, v253, 54
	v_readlane_b32 s21, v253, 55
	v_ashrrev_i32_e32 v129, 31, v128
	v_or_b32_e32 v160, v141, v145
	v_lshl_add_u64 v[130:131], s[20:21], 0, v[136:137]
	v_lshl_add_u64 v[128:129], v[128:129], 2, v[130:131]
	s_waitcnt vmcnt(0)
	v_mov_b32_e32 v128, v214
	v_mov_b32_e32 v129, v215
	v_mov_b32_e32 v130, v216
	v_mov_b32_e32 v131, v217
	v_lshrrev_b32_e32 v160, 3, v160
	s_mov_b64 s[20:21], -1
	s_andn2_b64 vcc, exec, s[16:17]
	v_xor_b32_e32 v160, v160, v150
	s_cbranch_vccnz .LBB0_1677
	s_waitcnt vmcnt(0)
	v_mul_f32_e32 v161, 0xbfb8aa3b, v128
	v_exp_f32_e32 v162, v161
	v_mul_f32_e32 v161, 0xbfb8aa3b, v129
	v_exp_f32_e32 v163, v161
	v_mul_f32_e32 v161, 0xbfb8aa3b, v130
	v_exp_f32_e32 v164, v161
	v_mul_f32_e32 v161, 0xbfb8aa3b, v131
	v_exp_f32_e32 v165, v161
	v_pk_mul_f32 v[162:163], v[100:101], v[162:163]
	v_lshlrev_b32_e32 v161, 4, v160
	v_cvt_pk_bf16_f32 v162, v162, v163
	v_pk_mul_f32 v[164:165], v[102:103], v[164:165]
	s_mov_b64 s[20:21], 0
	v_cvt_pk_bf16_f32 v163, v164, v165
	v_lshlrev_b32_e32 v164, 3, v140
	v_add3_u32 v161, v159, v161, v164
	ds_write_b64 v161, v[162:163]

; DEV u32x2 pk4(f32x4 v) { u32x2 r = {pk_bf16(v[0], v[1]), pk_bf16(v[2], v[3])}; return r; }
; DEV int sig4(int x) { return ((x & 1) << 1) | (x >> 1); }
;   DEV void operator()(f32x4 (&acc)[2][2][4][2], int brow, int bcol, int wr, int wc, int fr, int fq) const {
;     ...
;               const f32x4 b4 = *(const f32x4*)(bmat + (size_t)tok * 1024 + lc);
;               const int pcl = (cl & ~15) + 4 * sig4((cl >> 2) & 3);
;               if (mode == 3) {
;                 for (int j = 0; j < 4; ++j) v[j] = v[j] * scale * __expf(b4[j]);
;                 tile_put4(rl, pcl, pk4(v));
;               } else {
;                 const f32x4 bl = *(const f32x4*)(bmat + (size_t)(tok | 63) * 1024 + lc);
;                 f32x4 kd, ke;
;                 for (int j = 0; j < 4; ++j) { kd[j] = v[j] * __expf(-b4[j]); ke[j] = v[j] * __expf(bl[j] - b4[j]); }
;                 tile_put4(rl, pcl, pk4(kd));
.LBB0_1687:
	s_cmp_lt_i32 s37, 2
	s_cbranch_scc1 .LBB0_1697
	s_cmp_lg_u32 s37, 2
	s_cbranch_scc0 .LBB0_1694
	s_sub_i32 s20, s7, s36
	s_waitcnt vmcnt(0)
	v_add_u32_e32 v128, s20, v149
	v_readlane_b32 s20, v253, 54
	v_readlane_b32 s21, v253, 55
	v_ashrrev_i32_e32 v129, 31, v128
	s_andn2_b64 vcc, exec, s[16:17]
	v_lshl_add_u64 v[130:131], s[20:21], 0, v[136:137]
	v_lshl_add_u64 v[128:129], v[128:129], 2, v[130:131]
	s_waitcnt vmcnt(0)
	v_mov_b32_e32 v128, v224
	v_mov_b32_e32 v129, v225
	v_mov_b32_e32 v130, v226
	v_mov_b32_e32 v131, v227
	v_or_b32_e32 v136, v141, v147
	v_lshrrev_b32_e32 v136, 3, v136
	s_mov_b64 s[20:21], -1
	v_xor_b32_e32 v136, v136, v150
	s_cbranch_vccnz .LBB0_1691
	s_waitcnt vmcnt(0)
	v_mul_f32_e32 v137, 0xbfb8aa3b, v128
	v_exp_f32_e32 v160, v137
	v_mul_f32_e32 v137, 0xbfb8aa3b, v129
	v_exp_f32_e32 v161, v137
	v_mul_f32_e32 v137, 0xbfb8aa3b, v130
	v_exp_f32_e32 v162, v137
	v_mul_f32_e32 v137, 0xbfb8aa3b, v131
	v_exp_f32_e32 v163, v137
	v_pk_mul_f32 v[160:161], v[96:97], v[160:161]
	v_lshlrev_b32_e32 v137, 4, v136
	v_cvt_pk_bf16_f32 v160, v160, v161
	v_pk_mul_f32 v[162:163], v[98:99], v[162:163]
	s_mov_b64 s[20:21], 0
	v_cvt_pk_bf16_f32 v161, v162, v163
	v_lshlrev_b32_e32 v162, 3, v140
	v_add3_u32 v137, v159, v137, v162
	ds_write_b64 v137, v[160:161]

; DEV u32x2 pk4(f32x4 v) { u32x2 r = {pk_bf16(v[0], v[1]), pk_bf16(v[2], v[3])}; return r; }
; DEV int sig4(int x) { return ((x & 1) << 1) | (x >> 1); }
;   DEV void operator()(f32x4 (&acc)[2][2][4][2], int brow, int bcol, int wr, int wc, int fr, int fq) const {
;     ...
;               const f32x4 b4 = *(const f32x4*)(bmat + (size_t)tok * 1024 + lc);
;               const int pcl = (cl & ~15) + 4 * sig4((cl >> 2) & 3);
;               if (mode == 3) {
;                 for (int j = 0; j < 4; ++j) v[j] = v[j] * scale * __expf(b4[j]);
;                 tile_put4(rl, pcl, pk4(v));
;               } else {
;                 const f32x4 bl = *(const f32x4*)(bmat + (size_t)(tok | 63) * 1024 + lc);
;                 f32x4 kd, ke;
;                 for (int j = 0; j < 4; ++j) { kd[j] = v[j] * __expf(-b4[j]); ke[j] = v[j] * __expf(bl[j] - b4[j]); }
;                 tile_put4(rl, pcl, pk4(kd));
.LBB0_1708:
	s_waitcnt vmcnt(0)
	v_or_b32_e32 v129, 32, v144
	v_add_u32_e32 v128, s5, v129
	v_lshl_add_u32 v159, v129, 9, 0
	v_ashrrev_i32_e32 v129, 31, v128
	v_lshlrev_b64 v[136:137], 12, v[128:129]
	s_cmp_lt_i32 s37, 1
	s_mov_b64 s[20:21], -1
	s_cbranch_scc1 .LBB0_1764
	s_cmp_lt_i32 s37, 2
	s_cbranch_scc1 .LBB0_1719
	s_cmp_lg_u32 s37, 2
	s_cbranch_scc0 .LBB0_1716
	v_add_u32_e32 v128, s7, v203
	v_readlane_b32 s20, v253, 54
	v_subrev_u32_e32 v128, s36, v128
	v_readlane_b32 s21, v253, 55
	v_ashrrev_i32_e32 v129, 31, v128
	v_or_b32_e32 v160, v141, v142
	v_lshl_add_u64 v[130:131], s[20:21], 0, v[136:137]
	v_lshl_add_u64 v[128:129], v[128:129], 2, v[130:131]
	s_waitcnt vmcnt(0)
	v_mov_b32_e32 v128, v228
	v_mov_b32_e32 v129, v229
	v_mov_b32_e32 v130, v230
	v_mov_b32_e32 v131, v231
	v_lshrrev_b32_e32 v160, 3, v160
	s_mov_b64 s[20:21], -1
	s_andn2_b64 vcc, exec, s[16:17]
	v_xor_b32_e32 v160, v160, v201
	s_cbranch_vccnz .LBB0_1713
	s_waitcnt vmcnt(0)
	v_mul_f32_e32 v161, 0xbfb8aa3b, v128
	v_exp_f32_e32 v162, v161
	v_mul_f32_e32 v161, 0xbfb8aa3b, v129
	v_exp_f32_e32 v163, v161
	v_mul_f32_e32 v161, 0xbfb8aa3b, v130
	v_exp_f32_e32 v164, v161
	v_mul_f32_e32 v161, 0xbfb8aa3b, v131
	v_exp_f32_e32 v165, v161
	v_pk_mul_f32 v[162:163], v[92:93], v[162:163]
	v_lshlrev_b32_e32 v161, 4, v160
	v_cvt_pk_bf16_f32 v162, v162, v163
	v_pk_mul_f32 v[164:165], v[94:95], v[164:165]
	s_mov_b64 s[20:21], 0
	v_cvt_pk_bf16_f32 v163, v164, v165
	v_lshlrev_b32_e32 v164, 3, v140
	v_add3_u32 v161, v159, v161, v164
	ds_write_b64 v161, v[162:163]

; DEV u32x2 pk4(f32x4 v) { u32x2 r = {pk_bf16(v[0], v[1]), pk_bf16(v[2], v[3])}; return r; }
; DEV int sig4(int x) { return ((x & 1) << 1) | (x >> 1); }
;   DEV void operator()(f32x4 (&acc)[2][2][4][2], int brow, int bcol, int wr, int wc, int fr, int fq) const {
;     ...
;               const f32x4 b4 = *(const f32x4*)(bmat + (size_t)tok * 1024 + lc);
;               const int pcl = (cl & ~15) + 4 * sig4((cl >> 2) & 3);
;               if (mode == 3) {
;                 for (int j = 0; j < 4; ++j) v[j] = v[j] * scale * __expf(b4[j]);
;                 tile_put4(rl, pcl, pk4(v));
;               } else {
;                 const f32x4 bl = *(const f32x4*)(bmat + (size_t)(tok | 63) * 1024 + lc);
;                 f32x4 kd, ke;
;                 for (int j = 0; j < 4; ++j) { kd[j] = v[j] * __expf(-b4[j]); ke[j] = v[j] * __expf(bl[j] - b4[j]); }
;                 tile_put4(rl, pcl, pk4(kd));
.LBB0_1723:
	s_cmp_lt_i32 s37, 2
	s_cbranch_scc1 .LBB0_1733
	s_cmp_lg_u32 s37, 2
	s_cbranch_scc0 .LBB0_1730
	s_sub_i32 s20, s7, s36
	s_waitcnt vmcnt(0)
	v_add_u32_e32 v128, s20, v146
	v_readlane_b32 s20, v253, 54
	v_readlane_b32 s21, v253, 55
	v_ashrrev_i32_e32 v129, 31, v128
	v_or_b32_e32 v160, v141, v143
	v_lshl_add_u64 v[130:131], s[20:21], 0, v[136:137]
	v_lshl_add_u64 v[128:129], v[128:129], 2, v[130:131]
	s_waitcnt vmcnt(0)
	v_mov_b32_e32 v128, v232
	v_mov_b32_e32 v129, v233
	v_mov_b32_e32 v130, v234
	v_mov_b32_e32 v131, v235
	v_lshrrev_b32_e32 v160, 3, v160
	s_mov_b64 s[20:21], -1
	s_andn2_b64 vcc, exec, s[16:17]
	v_xor_b32_e32 v160, v160, v201
	s_cbranch_vccnz .LBB0_1727
	s_waitcnt vmcnt(0)
	v_mul_f32_e32 v161, 0xbfb8aa3b, v128
	v_exp_f32_e32 v162, v161
	v_mul_f32_e32 v161, 0xbfb8aa3b, v129
	v_exp_f32_e32 v163, v161
	v_mul_f32_e32 v161, 0xbfb8aa3b, v130
	v_exp_f32_e32 v164, v161
	v_mul_f32_e32 v161, 0xbfb8aa3b, v131
	v_exp_f32_e32 v165, v161
	v_pk_mul_f32 v[162:163], v[88:89], v[162:163]
	v_lshlrev_b32_e32 v161, 4, v160
	v_cvt_pk_bf16_f32 v162, v162, v163
	v_pk_mul_f32 v[164:165], v[90:91], v[164:165]
	s_mov_b64 s[20:21], 0
	v_cvt_pk_bf16_f32 v163, v164, v165
	v_lshlrev_b32_e32 v164, 3, v140
	v_add3_u32 v161, v159, v161, v164
	ds_write_b64 v161, v[162:163]

; DEV u32x2 pk4(f32x4 v) { u32x2 r = {pk_bf16(v[0], v[1]), pk_bf16(v[2], v[3])}; return r; }
; DEV int sig4(int x) { return ((x & 1) << 1) | (x >> 1); }
;   DEV void operator()(f32x4 (&acc)[2][2][4][2], int brow, int bcol, int wr, int wc, int fr, int fq) const {
;     ...
;               const f32x4 b4 = *(const f32x4*)(bmat + (size_t)tok * 1024 + lc);
;               const int pcl = (cl & ~15) + 4 * sig4((cl >> 2) & 3);
;               if (mode == 3) {
;                 for (int j = 0; j < 4; ++j) v[j] = v[j] * scale * __expf(b4[j]);
;                 tile_put4(rl, pcl, pk4(v));
;               } else {
;                 const f32x4 bl = *(const f32x4*)(bmat + (size_t)(tok | 63) * 1024 + lc);
;                 f32x4 kd, ke;
;                 for (int j = 0; j < 4; ++j) { kd[j] = v[j] * __expf(-b4[j]); ke[j] = v[j] * __expf(bl[j] - b4[j]); }
;                 tile_put4(rl, pcl, pk4(kd));
.LBB0_1737:
	s_cmp_lt_i32 s37, 2
	s_cbranch_scc1 .LBB0_1747
	s_cmp_lg_u32 s37, 2
	s_cbranch_scc0 .LBB0_1744
	s_sub_i32 s20, s7, s36
	s_waitcnt vmcnt(0)
	v_add_u32_e32 v128, s20, v148
	v_readlane_b32 s20, v253, 54
	v_readlane_b32 s21, v253, 55
	v_ashrrev_i32_e32 v129, 31, v128
	v_or_b32_e32 v160, v141, v145
	v_lshl_add_u64 v[130:131], s[20:21], 0, v[136:137]
	v_lshl_add_u64 v[128:129], v[128:129], 2, v[130:131]
	s_waitcnt vmcnt(0)
	v_mov_b32_e32 v128, v236
	v_mov_b32_e32 v129, v237
	v_mov_b32_e32 v130, v238
	v_mov_b32_e32 v131, v239
	v_lshrrev_b32_e32 v160, 3, v160
	s_mov_b64 s[20:21], -1
	s_andn2_b64 vcc, exec, s[16:17]
	v_xor_b32_e32 v160, v160, v201
	s_cbranch_vccnz .LBB0_1741
	s_waitcnt vmcnt(0)
	v_mul_f32_e32 v161, 0xbfb8aa3b, v128
	v_exp_f32_e32 v162, v161
	v_mul_f32_e32 v161, 0xbfb8aa3b, v129
	v_exp_f32_e32 v163, v161
	v_mul_f32_e32 v161, 0xbfb8aa3b, v130
	v_exp_f32_e32 v164, v161
	v_mul_f32_e32 v161, 0xbfb8aa3b, v131
	v_exp_f32_e32 v165, v161
	v_pk_mul_f32 v[162:163], v[84:85], v[162:163]
	v_lshlrev_b32_e32 v161, 4, v160
	v_cvt_pk_bf16_f32 v162, v162, v163
	v_pk_mul_f32 v[164:165], v[86:87], v[164:165]
	s_mov_b64 s[20:21], 0
	v_cvt_pk_bf16_f32 v163, v164, v165
	v_lshlrev_b32_e32 v164, 3, v140
	v_add3_u32 v161, v159, v161, v164
	ds_write_b64 v161, v[162:163]

; DEV u32x2 pk4(f32x4 v) { u32x2 r = {pk_bf16(v[0], v[1]), pk_bf16(v[2], v[3])}; return r; }
; DEV int sig4(int x) { return ((x & 1) << 1) | (x >> 1); }
;   DEV void operator()(f32x4 (&acc)[2][2][4][2], int brow, int bcol, int wr, int wc, int fr, int fq) const {
;     ...
;               const f32x4 b4 = *(const f32x4*)(bmat + (size_t)tok * 1024 + lc);
;               const int pcl = (cl & ~15) + 4 * sig4((cl >> 2) & 3);
;               if (mode == 3) {
;                 for (int j = 0; j < 4; ++j) v[j] = v[j] * scale * __expf(b4[j]);
;                 tile_put4(rl, pcl, pk4(v));
;               } else {
;                 const f32x4 bl = *(const f32x4*)(bmat + (size_t)(tok | 63) * 1024 + lc);
;                 f32x4 kd, ke;
;                 for (int j = 0; j < 4; ++j) { kd[j] = v[j] * __expf(-b4[j]); ke[j] = v[j] * __expf(bl[j] - b4[j]); }
;                 tile_put4(rl, pcl, pk4(kd));
.LBB0_1751:
	s_cmp_lt_i32 s37, 2
	s_cbranch_scc1 .LBB0_1761
	s_cmp_lg_u32 s37, 2
	s_cbranch_scc0 .LBB0_1758
	s_sub_i32 s20, s7, s36
	s_waitcnt vmcnt(0)
	v_add_u32_e32 v128, s20, v149
	v_readlane_b32 s20, v253, 54
	v_readlane_b32 s21, v253, 55
	v_ashrrev_i32_e32 v129, 31, v128
	s_andn2_b64 vcc, exec, s[16:17]
	v_lshl_add_u64 v[130:131], s[20:21], 0, v[136:137]
	v_lshl_add_u64 v[128:129], v[128:129], 2, v[130:131]
	s_waitcnt vmcnt(0)
	v_mov_b32_e32 v128, v240
	v_mov_b32_e32 v129, v241
	v_mov_b32_e32 v130, v242
	v_mov_b32_e32 v131, v243
	v_or_b32_e32 v136, v141, v147
	v_lshrrev_b32_e32 v136, 3, v136
	s_mov_b64 s[20:21], -1
	v_xor_b32_e32 v136, v136, v201
	s_cbranch_vccnz .LBB0_1755
	s_waitcnt vmcnt(0)
	v_mul_f32_e32 v137, 0xbfb8aa3b, v128
	v_exp_f32_e32 v160, v137
	v_mul_f32_e32 v137, 0xbfb8aa3b, v129
	v_exp_f32_e32 v161, v137
	v_mul_f32_e32 v137, 0xbfb8aa3b, v130
	v_exp_f32_e32 v162, v137
	v_mul_f32_e32 v137, 0xbfb8aa3b, v131
	v_exp_f32_e32 v163, v137
	v_pk_mul_f32 v[160:161], v[80:81], v[160:161]
	v_lshlrev_b32_e32 v137, 4, v136
	v_cvt_pk_bf16_f32 v160, v160, v161
	v_pk_mul_f32 v[162:163], v[82:83], v[162:163]
	s_mov_b64 s[20:21], 0
	v_cvt_pk_bf16_f32 v161, v162, v163
	v_lshlrev_b32_e32 v162, 3, v140
	v_add3_u32 v137, v159, v137, v162
	ds_write_b64 v137, v[160:161]

; DEV u32x2 pk4(f32x4 v) { u32x2 r = {pk_bf16(v[0], v[1]), pk_bf16(v[2], v[3])}; return r; }
; DEV int sig4(int x) { return ((x & 1) << 1) | (x >> 1); }
;   DEV void operator()(f32x4 (&acc)[2][2][4][2], int brow, int bcol, int wr, int wc, int fr, int fq) const {
;     ...
;               const f32x4 b4 = *(const f32x4*)(bmat + (size_t)tok * 1024 + lc);
;               const int pcl = (cl & ~15) + 4 * sig4((cl >> 2) & 3);
;               if (mode == 3) {
;                 for (int j = 0; j < 4; ++j) v[j] = v[j] * scale * __expf(b4[j]);
;                 tile_put4(rl, pcl, pk4(v));
;               } else {
;                 const f32x4 bl = *(const f32x4*)(bmat + (size_t)(tok | 63) * 1024 + lc);
;                 f32x4 kd, ke;
;                 for (int j = 0; j < 4; ++j) { kd[j] = v[j] * __expf(-b4[j]); ke[j] = v[j] * __expf(bl[j] - b4[j]); }
;                 tile_put4(rl, pcl, pk4(kd));
.LBB0_1772:
	s_waitcnt vmcnt(0)
	v_or_b32_e32 v129, 48, v144
	v_add_u32_e32 v128, s5, v129
	v_lshl_add_u32 v159, v129, 9, 0
	v_ashrrev_i32_e32 v129, 31, v128
	v_lshlrev_b64 v[136:137], 12, v[128:129]
	s_cmp_lt_i32 s37, 1
	s_mov_b64 s[20:21], -1
	s_cbranch_scc1 .LBB0_1828
	s_cmp_lt_i32 s37, 2
	s_cbranch_scc1 .LBB0_1783
	s_cmp_lg_u32 s37, 2
	s_cbranch_scc0 .LBB0_1780
	v_add_u32_e32 v128, s7, v203
	v_readlane_b32 s20, v253, 54
	v_subrev_u32_e32 v128, s36, v128
	v_readlane_b32 s21, v253, 55
	v_ashrrev_i32_e32 v129, 31, v128
	v_or_b32_e32 v160, v141, v142
	v_lshl_add_u64 v[130:131], s[20:21], 0, v[136:137]
	v_lshl_add_u64 v[128:129], v[128:129], 2, v[130:131]
	s_waitcnt vmcnt(0)
	v_mov_b32_e32 v128, v244
	v_mov_b32_e32 v129, v245
	v_mov_b32_e32 v130, v246
	v_mov_b32_e32 v131, v247
	v_lshrrev_b32_e32 v160, 3, v160
	s_mov_b64 s[20:21], -1
	s_andn2_b64 vcc, exec, s[16:17]
	v_xor_b32_e32 v160, v160, v150
	s_cbranch_vccnz .LBB0_1777
	s_waitcnt vmcnt(0)
	v_mul_f32_e32 v161, 0xbfb8aa3b, v128
	v_exp_f32_e32 v162, v161
	v_mul_f32_e32 v161, 0xbfb8aa3b, v129
	v_exp_f32_e32 v163, v161
	v_mul_f32_e32 v161, 0xbfb8aa3b, v130
	v_exp_f32_e32 v164, v161
	v_mul_f32_e32 v161, 0xbfb8aa3b, v131
	v_exp_f32_e32 v165, v161
	v_pk_mul_f32 v[162:163], v[76:77], v[162:163]
	v_lshlrev_b32_e32 v161, 4, v160
	v_cvt_pk_bf16_f32 v162, v162, v163
	v_pk_mul_f32 v[164:165], v[78:79], v[164:165]
	s_mov_b64 s[20:21], 0
	v_cvt_pk_bf16_f32 v163, v164, v165
	v_lshlrev_b32_e32 v164, 3, v140
	v_add3_u32 v161, v159, v161, v164
	ds_write_b64 v161, v[162:163]

; DEV u32x2 pk4(f32x4 v) { u32x2 r = {pk_bf16(v[0], v[1]), pk_bf16(v[2], v[3])}; return r; }
; DEV int sig4(int x) { return ((x & 1) << 1) | (x >> 1); }
;   DEV void operator()(f32x4 (&acc)[2][2][4][2], int brow, int bcol, int wr, int wc, int fr, int fq) const {
;     ...
;               const f32x4 b4 = *(const f32x4*)(bmat + (size_t)tok * 1024 + lc);
;               const int pcl = (cl & ~15) + 4 * sig4((cl >> 2) & 3);
;               if (mode == 3) {
;                 for (int j = 0; j < 4; ++j) v[j] = v[j] * scale * __expf(b4[j]);
;                 tile_put4(rl, pcl, pk4(v));
;               } else {
;                 const f32x4 bl = *(const f32x4*)(bmat + (size_t)(tok | 63) * 1024 + lc);
;                 f32x4 kd, ke;
;                 for (int j = 0; j < 4; ++j) { kd[j] = v[j] * __expf(-b4[j]); ke[j] = v[j] * __expf(bl[j] - b4[j]); }
;                 tile_put4(rl, pcl, pk4(kd));
.LBB0_1787:
	s_cmp_lt_i32 s37, 2
	s_cbranch_scc1 .LBB0_1797
	s_cmp_lg_u32 s37, 2
	s_cbranch_scc0 .LBB0_1794
	s_sub_i32 s20, s7, s36
	s_waitcnt vmcnt(0)
	v_add_u32_e32 v128, s20, v146
	v_readlane_b32 s20, v253, 54
	v_readlane_b32 s21, v253, 55
	v_ashrrev_i32_e32 v129, 31, v128
	v_or_b32_e32 v160, v141, v143
	v_lshl_add_u64 v[130:131], s[20:21], 0, v[136:137]
	v_lshl_add_u64 v[128:129], v[128:129], 2, v[130:131]
	s_waitcnt vmcnt(0)
	v_mov_b32_e32 v128, v248
	v_mov_b32_e32 v129, v249
	v_mov_b32_e32 v130, v250
	v_mov_b32_e32 v131, v251
	v_lshrrev_b32_e32 v160, 3, v160
	s_mov_b64 s[20:21], -1
	s_andn2_b64 vcc, exec, s[16:17]
	v_xor_b32_e32 v160, v160, v150
	s_cbranch_vccnz .LBB0_1791
	s_waitcnt vmcnt(0)
	v_mul_f32_e32 v161, 0xbfb8aa3b, v128
	v_exp_f32_e32 v162, v161
	v_mul_f32_e32 v161, 0xbfb8aa3b, v129
	v_exp_f32_e32 v163, v161
	v_mul_f32_e32 v161, 0xbfb8aa3b, v130
	v_exp_f32_e32 v164, v161
	v_mul_f32_e32 v161, 0xbfb8aa3b, v131
	v_exp_f32_e32 v165, v161
	v_pk_mul_f32 v[162:163], v[72:73], v[162:163]
	v_lshlrev_b32_e32 v161, 4, v160
	v_cvt_pk_bf16_f32 v162, v162, v163
	v_pk_mul_f32 v[164:165], v[74:75], v[164:165]
	s_mov_b64 s[20:21], 0
	v_cvt_pk_bf16_f32 v163, v164, v165
	v_lshlrev_b32_e32 v164, 3, v140
	v_add3_u32 v161, v159, v161, v164
	ds_write_b64 v161, v[162:163]

; DEV u32x2 pk4(f32x4 v) { u32x2 r = {pk_bf16(v[0], v[1]), pk_bf16(v[2], v[3])}; return r; }
; DEV int sig4(int x) { return ((x & 1) << 1) | (x >> 1); }
;   DEV void operator()(f32x4 (&acc)[2][2][4][2], int brow, int bcol, int wr, int wc, int fr, int fq) const {
;     ...
;               const f32x4 b4 = *(const f32x4*)(bmat + (size_t)tok * 1024 + lc);
;               const int pcl = (cl & ~15) + 4 * sig4((cl >> 2) & 3);
;               if (mode == 3) {
;                 for (int j = 0; j < 4; ++j) v[j] = v[j] * scale * __expf(b4[j]);
;                 tile_put4(rl, pcl, pk4(v));
;               } else {
;                 const f32x4 bl = *(const f32x4*)(bmat + (size_t)(tok | 63) * 1024 + lc);
;                 f32x4 kd, ke;
;                 for (int j = 0; j < 4; ++j) { kd[j] = v[j] * __expf(-b4[j]); ke[j] = v[j] * __expf(bl[j] - b4[j]); }
;                 tile_put4(rl, pcl, pk4(kd));
.LBB0_1801:
	s_cmp_lt_i32 s37, 2
	s_cbranch_scc1 .LBB0_1811
	s_cmp_lg_u32 s37, 2
	s_cbranch_scc0 .LBB0_1808
	s_sub_i32 s20, s7, s36
	s_waitcnt vmcnt(0)
	v_add_u32_e32 v128, s20, v148
	v_readlane_b32 s20, v253, 54
	v_readlane_b32 s21, v253, 55
	v_ashrrev_i32_e32 v129, 31, v128
	v_or_b32_e32 v160, v141, v145
	v_lshl_add_u64 v[130:131], s[20:21], 0, v[136:137]
	v_lshl_add_u64 v[128:129], v[128:129], 2, v[130:131]
	s_waitcnt vmcnt(0)
	v_mov_b32_e32 v128, v166
	v_mov_b32_e32 v129, v167
	v_mov_b32_e32 v130, v168
	v_mov_b32_e32 v131, v169
	v_lshrrev_b32_e32 v160, 3, v160
	s_mov_b64 s[20:21], -1
	s_andn2_b64 vcc, exec, s[16:17]
	v_xor_b32_e32 v160, v160, v150
	s_cbranch_vccnz .LBB0_1805
	s_waitcnt vmcnt(0)
	v_mul_f32_e32 v161, 0xbfb8aa3b, v128
	v_exp_f32_e32 v162, v161
	v_mul_f32_e32 v161, 0xbfb8aa3b, v129
	v_exp_f32_e32 v163, v161
	v_mul_f32_e32 v161, 0xbfb8aa3b, v130
	v_exp_f32_e32 v164, v161
	v_mul_f32_e32 v161, 0xbfb8aa3b, v131
	v_exp_f32_e32 v165, v161
	v_pk_mul_f32 v[162:163], v[68:69], v[162:163]
	v_lshlrev_b32_e32 v161, 4, v160
	v_cvt_pk_bf16_f32 v162, v162, v163
	v_pk_mul_f32 v[164:165], v[70:71], v[164:165]
	s_mov_b64 s[20:21], 0
	v_cvt_pk_bf16_f32 v163, v164, v165
	v_lshlrev_b32_e32 v164, 3, v140
	v_add3_u32 v161, v159, v161, v164
	ds_write_b64 v161, v[162:163]

; DEV u32x2 pk4(f32x4 v) { u32x2 r = {pk_bf16(v[0], v[1]), pk_bf16(v[2], v[3])}; return r; }
; DEV int sig4(int x) { return ((x & 1) << 1) | (x >> 1); }
;   DEV void operator()(f32x4 (&acc)[2][2][4][2], int brow, int bcol, int wr, int wc, int fr, int fq) const {
;     ...
;               const f32x4 b4 = *(const f32x4*)(bmat + (size_t)tok * 1024 + lc);
;               const int pcl = (cl & ~15) + 4 * sig4((cl >> 2) & 3);
;               if (mode == 3) {
;                 for (int j = 0; j < 4; ++j) v[j] = v[j] * scale * __expf(b4[j]);
;                 tile_put4(rl, pcl, pk4(v));
;               } else {
;                 const f32x4 bl = *(const f32x4*)(bmat + (size_t)(tok | 63) * 1024 + lc);
;                 f32x4 kd, ke;
;                 for (int j = 0; j < 4; ++j) { kd[j] = v[j] * __expf(-b4[j]); ke[j] = v[j] * __expf(bl[j] - b4[j]); }
;                 tile_put4(rl, pcl, pk4(kd));
.LBB0_1815:
	s_cmp_lt_i32 s37, 2
	s_cbranch_scc1 .LBB0_1825
	s_cmp_lg_u32 s37, 2
	s_cbranch_scc0 .LBB0_1822
	s_sub_i32 s20, s7, s36
	s_waitcnt vmcnt(0)
	v_add_u32_e32 v128, s20, v149
	v_readlane_b32 s20, v253, 54
	v_readlane_b32 s21, v253, 55
	v_ashrrev_i32_e32 v129, 31, v128
	s_andn2_b64 vcc, exec, s[16:17]
	v_lshl_add_u64 v[130:131], s[20:21], 0, v[136:137]
	v_lshl_add_u64 v[128:129], v[128:129], 2, v[130:131]
	s_waitcnt vmcnt(0)
	v_mov_b32_e32 v128, v170
	v_mov_b32_e32 v129, v171
	v_mov_b32_e32 v130, v172
	v_mov_b32_e32 v131, v173
	v_or_b32_e32 v136, v141, v147
	v_lshrrev_b32_e32 v136, 3, v136
	s_mov_b64 s[20:21], -1
	v_xor_b32_e32 v136, v136, v150
	s_cbranch_vccnz .LBB0_1819
	s_waitcnt vmcnt(0)
	v_mul_f32_e32 v137, 0xbfb8aa3b, v128
	v_exp_f32_e32 v160, v137
	v_mul_f32_e32 v137, 0xbfb8aa3b, v129
	v_exp_f32_e32 v161, v137
	v_mul_f32_e32 v137, 0xbfb8aa3b, v130
	v_exp_f32_e32 v162, v137
	v_mul_f32_e32 v137, 0xbfb8aa3b, v131
	v_exp_f32_e32 v163, v137
	v_pk_mul_f32 v[160:161], v[64:65], v[160:161]
	v_lshlrev_b32_e32 v137, 4, v136
	v_cvt_pk_bf16_f32 v160, v160, v161
	v_pk_mul_f32 v[162:163], v[66:67], v[162:163]
	s_mov_b64 s[20:21], 0
	v_cvt_pk_bf16_f32 v161, v162, v163
	v_lshlrev_b32_e32 v162, 3, v140
	v_add3_u32 v137, v159, v137, v162
	ds_write_b64 v137, v[160:161]

; DEV u32x2 pk4(f32x4 v) { u32x2 r = {pk_bf16(v[0], v[1]), pk_bf16(v[2], v[3])}; return r; }
; DEV int sig4(int x) { return ((x & 1) << 1) | (x >> 1); }
; DEV float fsigmoid(float x) { return 1.f / (1.f + __expf(-x)); }
;   DEV void operator()(f32x4 (&acc)[2][2][4][2], int brow, int bcol, int wr, int wc, int fr, int fq) const {
;     ...
;     for (int ai = 0; ai < 2; ++ai)
; #pragma unroll
;       for (int m = 0; m < 4; ++m) {
;         const int rl = ai * 128 + wr * 64 + m * 16 + fr, tok = brow + rl;
; #pragma unroll
;         for (int bj = 0; bj < 2; ++bj)
; #pragma unroll
;           for (int n = 0; n < 2; ++n) {
;             const int cl = bj * 128 + wc * 32 + n * 16 + fq * 4, lc = bcol - segstart + cl;
;             f32x4 v = acc[ai][bj][m][n];
;             if (mode == 0) {
;               tile_put4(rl, cl, pk4(v * scale));
;             } else if (mode == 1) {
;               for (int j = 0; j < 4; ++j) v[j] = v[j] * fsigmoid(v[j]);
;               tile_put4(rl, cl, pk4(v));
;             } else if (mode == 2) {
;               for (int j = 0; j < 4; ++j) v[j] = fsigmoid(v[j]);
;               tile_put4(rl, cl, pk4(v));
;             } else {
;               const f32x4 b4 = *(const f32x4*)(bmat + (size_t)tok * 1024 + lc);
;               const int pcl = (cl & ~15) + 4 * sig4((cl >> 2) & 3);
;               if (mode == 3) {
;                 for (int j = 0; j < 4; ++j) v[j] = v[j] * scale * __expf(b4[j]);
;                 tile_put4(rl, pcl, pk4(v));
;               } else {
;                 const f32x4 bl = *(const f32x4*)(bmat + (size_t)(tok | 63) * 1024 + lc);
;                 f32x4 kd, ke;
;                 for (int j = 0; j < 4; ++j) { kd[j] = v[j] * __expf(-b4[j]); ke[j] = v[j] * __expf(bl[j] - b4[j]); }
;                 tile_put4(rl, pcl, pk4(kd));
.LBB0_1836:
	s_waitcnt vmcnt(0)
	v_add_u32_e32 v129, 0x80, v144
	v_add_u32_e32 v128, s5, v129
	v_lshl_add_u32 v159, v129, 9, 0
	v_ashrrev_i32_e32 v129, 31, v128
	v_lshlrev_b64 v[136:137], 12, v[128:129]
	s_cmp_lt_i32 s37, 1
	s_mov_b64 s[20:21], -1
	s_cbranch_scc1 .LBB0_1892
	s_cmp_lt_i32 s37, 2
	s_cbranch_scc1 .LBB0_1847
	s_cmp_lg_u32 s37, 2
	s_cbranch_scc0 .LBB0_1844
	v_readlane_b32 s20, v253, 54
	v_readlane_b32 s21, v253, 55
	v_add_u32_e32 v175, 0x40000, v175
	s_nop 3
	global_load_dwordx4 v[180:183], v175, s[20:21]
	global_load_dwordx4 v[184:187], v175, s[20:21] offset:64
	global_load_dwordx4 v[188:191], v175, s[20:21] offset:512
	global_load_dwordx4 v[192:195], v175, s[20:21] offset:576
	v_add_u32_e32 v175, 0x10000, v175
	global_load_dwordx4 v[206:209], v175, s[20:21]
	global_load_dwordx4 v[210:213], v175, s[20:21] offset:64
	global_load_dwordx4 v[214:217], v175, s[20:21] offset:512
	global_load_dwordx4 v[224:227], v175, s[20:21] offset:576
	v_add_u32_e32 v175, 0x10000, v175
	global_load_dwordx4 v[228:231], v175, s[20:21]
	global_load_dwordx4 v[232:235], v175, s[20:21] offset:64
	global_load_dwordx4 v[236:239], v175, s[20:21] offset:512
	global_load_dwordx4 v[240:243], v175, s[20:21] offset:576
	v_add_u32_e32 v175, 0x10000, v175
	global_load_dwordx4 v[244:247], v175, s[20:21]
	global_load_dwordx4 v[248:251], v175, s[20:21] offset:64
	global_load_dwordx4 v[166:169], v175, s[20:21] offset:512
	global_load_dwordx4 v[170:173], v175, s[20:21] offset:576
	v_add_u32_e32 v175, 0x10000, v175
	v_add_u32_e32 v128, s7, v203
	v_readlane_b32 s20, v253, 54
	v_subrev_u32_e32 v128, s36, v128
	v_readlane_b32 s21, v253, 55
	v_ashrrev_i32_e32 v129, 31, v128
	v_or_b32_e32 v160, v141, v142
	v_lshl_add_u64 v[130:131], s[20:21], 0, v[136:137]
	v_lshl_add_u64 v[128:129], v[128:129], 2, v[130:131]
	s_waitcnt vmcnt(0)
	v_mov_b32_e32 v128, v180
	v_mov_b32_e32 v129, v181
	v_mov_b32_e32 v130, v182
	v_mov_b32_e32 v131, v183
	v_lshrrev_b32_e32 v160, 3, v160
	s_mov_b64 s[20:21], -1
	s_andn2_b64 vcc, exec, s[16:17]
	v_xor_b32_e32 v160, v160, v201
	s_cbranch_vccnz .LBB0_1841
	s_waitcnt vmcnt(0)
	v_mul_f32_e32 v161, 0xbfb8aa3b, v128
	v_exp_f32_e32 v162, v161
	v_mul_f32_e32 v161, 0xbfb8aa3b, v129
	v_exp_f32_e32 v163, v161
	v_mul_f32_e32 v161, 0xbfb8aa3b, v130
	v_exp_f32_e32 v164, v161
	v_mul_f32_e32 v161, 0xbfb8aa3b, v131
	v_exp_f32_e32 v165, v161
	v_pk_mul_f32 v[162:163], v[60:61], v[162:163]
	v_lshlrev_b32_e32 v161, 4, v160
	v_cvt_pk_bf16_f32 v162, v162, v163
	v_pk_mul_f32 v[164:165], v[62:63], v[164:165]
	s_mov_b64 s[20:21], 0
	v_cvt_pk_bf16_f32 v163, v164, v165
	v_lshlrev_b32_e32 v164, 3, v140
	v_add3_u32 v161, v159, v161, v164
	ds_write_b64 v161, v[162:163]

; DEV u32x2 pk4(f32x4 v) { u32x2 r = {pk_bf16(v[0], v[1]), pk_bf16(v[2], v[3])}; return r; }
; DEV int sig4(int x) { return ((x & 1) << 1) | (x >> 1); }
;   DEV void operator()(f32x4 (&acc)[2][2][4][2], int brow, int bcol, int wr, int wc, int fr, int fq) const {
;     ...
;               const f32x4 b4 = *(const f32x4*)(bmat + (size_t)tok * 1024 + lc);
;               const int pcl = (cl & ~15) + 4 * sig4((cl >> 2) & 3);
;               if (mode == 3) {
;                 for (int j = 0; j < 4; ++j) v[j] = v[j] * scale * __expf(b4[j]);
;                 tile_put4(rl, pcl, pk4(v));
;               } else {
;                 const f32x4 bl = *(const f32x4*)(bmat + (size_t)(tok | 63) * 1024 + lc);
;                 f32x4 kd, ke;
;                 for (int j = 0; j < 4; ++j) { kd[j] = v[j] * __expf(-b4[j]); ke[j] = v[j] * __expf(bl[j] - b4[j]); }
;                 tile_put4(rl, pcl, pk4(kd));
.LBB0_1851:
	s_cmp_lt_i32 s37, 2
	s_cbranch_scc1 .LBB0_1861
	s_cmp_lg_u32 s37, 2
	s_cbranch_scc0 .LBB0_1858
	s_sub_i32 s20, s7, s36
	s_waitcnt vmcnt(0)
	v_add_u32_e32 v128, s20, v146
	v_readlane_b32 s20, v253, 54
	v_readlane_b32 s21, v253, 55
	v_ashrrev_i32_e32 v129, 31, v128
	v_or_b32_e32 v160, v141, v143
	v_lshl_add_u64 v[130:131], s[20:21], 0, v[136:137]
	v_lshl_add_u64 v[128:129], v[128:129], 2, v[130:131]
	s_waitcnt vmcnt(0)
	v_mov_b32_e32 v128, v184
	v_mov_b32_e32 v129, v185
	v_mov_b32_e32 v130, v186
	v_mov_b32_e32 v131, v187
	v_lshrrev_b32_e32 v160, 3, v160
	s_mov_b64 s[20:21], -1
	s_andn2_b64 vcc, exec, s[16:17]
	v_xor_b32_e32 v160, v160, v201
	s_cbranch_vccnz .LBB0_1855
	s_waitcnt vmcnt(0)
	v_mul_f32_e32 v161, 0xbfb8aa3b, v128
	v_exp_f32_e32 v162, v161
	v_mul_f32_e32 v161, 0xbfb8aa3b, v129
	v_exp_f32_e32 v163, v161
	v_mul_f32_e32 v161, 0xbfb8aa3b, v130
	v_exp_f32_e32 v164, v161
	v_mul_f32_e32 v161, 0xbfb8aa3b, v131
	v_exp_f32_e32 v165, v161
	v_pk_mul_f32 v[162:163], v[56:57], v[162:163]
	v_lshlrev_b32_e32 v161, 4, v160
	v_cvt_pk_bf16_f32 v162, v162, v163
	v_pk_mul_f32 v[164:165], v[58:59], v[164:165]
	s_mov_b64 s[20:21], 0
	v_cvt_pk_bf16_f32 v163, v164, v165
	v_lshlrev_b32_e32 v164, 3, v140
	v_add3_u32 v161, v159, v161, v164
	ds_write_b64 v161, v[162:163]

; DEV u32x2 pk4(f32x4 v) { u32x2 r = {pk_bf16(v[0], v[1]), pk_bf16(v[2], v[3])}; return r; }
; DEV int sig4(int x) { return ((x & 1) << 1) | (x >> 1); }
;   DEV void operator()(f32x4 (&acc)[2][2][4][2], int brow, int bcol, int wr, int wc, int fr, int fq) const {
;     ...
;               const f32x4 b4 = *(const f32x4*)(bmat + (size_t)tok * 1024 + lc);
;               const int pcl = (cl & ~15) + 4 * sig4((cl >> 2) & 3);
;               if (mode == 3) {
;                 for (int j = 0; j < 4; ++j) v[j] = v[j] * scale * __expf(b4[j]);
;                 tile_put4(rl, pcl, pk4(v));
;               } else {
;                 const f32x4 bl = *(const f32x4*)(bmat + (size_t)(tok | 63) * 1024 + lc);
;                 f32x4 kd, ke;
;                 for (int j = 0; j < 4; ++j) { kd[j] = v[j] * __expf(-b4[j]); ke[j] = v[j] * __expf(bl[j] - b4[j]); }
;                 tile_put4(rl, pcl, pk4(kd));
.LBB0_1865:
	s_cmp_lt_i32 s37, 2
	s_cbranch_scc1 .LBB0_1875
	s_cmp_lg_u32 s37, 2
	s_cbranch_scc0 .LBB0_1872
	s_sub_i32 s20, s7, s36
	s_waitcnt vmcnt(0)
	v_add_u32_e32 v128, s20, v148
	v_readlane_b32 s20, v253, 54
	v_readlane_b32 s21, v253, 55
	v_ashrrev_i32_e32 v129, 31, v128
	v_or_b32_e32 v160, v141, v145
	v_lshl_add_u64 v[130:131], s[20:21], 0, v[136:137]
	v_lshl_add_u64 v[128:129], v[128:129], 2, v[130:131]
	s_waitcnt vmcnt(0)
	v_mov_b32_e32 v128, v188
	v_mov_b32_e32 v129, v189
	v_mov_b32_e32 v130, v190
	v_mov_b32_e32 v131, v191
	v_lshrrev_b32_e32 v160, 3, v160
	s_mov_b64 s[20:21], -1
	s_andn2_b64 vcc, exec, s[16:17]
	v_xor_b32_e32 v160, v160, v201
	s_cbranch_vccnz .LBB0_1869
	s_waitcnt vmcnt(0)
	v_mul_f32_e32 v161, 0xbfb8aa3b, v128
	v_exp_f32_e32 v162, v161
	v_mul_f32_e32 v161, 0xbfb8aa3b, v129
	v_exp_f32_e32 v163, v161
	v_mul_f32_e32 v161, 0xbfb8aa3b, v130
	v_exp_f32_e32 v164, v161
	v_mul_f32_e32 v161, 0xbfb8aa3b, v131
	v_exp_f32_e32 v165, v161
	v_pk_mul_f32 v[162:163], v[52:53], v[162:163]
	v_lshlrev_b32_e32 v161, 4, v160
	v_cvt_pk_bf16_f32 v162, v162, v163
	v_pk_mul_f32 v[164:165], v[54:55], v[164:165]
	s_mov_b64 s[20:21], 0
	v_cvt_pk_bf16_f32 v163, v164, v165
	v_lshlrev_b32_e32 v164, 3, v140
	v_add3_u32 v161, v159, v161, v164
	ds_write_b64 v161, v[162:163]

; DEV u32x2 pk4(f32x4 v) { u32x2 r = {pk_bf16(v[0], v[1]), pk_bf16(v[2], v[3])}; return r; }
; DEV int sig4(int x) { return ((x & 1) << 1) | (x >> 1); }
;   DEV void operator()(f32x4 (&acc)[2][2][4][2], int brow, int bcol, int wr, int wc, int fr, int fq) const {
;     ...
;               const f32x4 b4 = *(const f32x4*)(bmat + (size_t)tok * 1024 + lc);
;               const int pcl = (cl & ~15) + 4 * sig4((cl >> 2) & 3);
;               if (mode == 3) {
;                 for (int j = 0; j < 4; ++j) v[j] = v[j] * scale * __expf(b4[j]);
;                 tile_put4(rl, pcl, pk4(v));
;               } else {
;                 const f32x4 bl = *(const f32x4*)(bmat + (size_t)(tok | 63) * 1024 + lc);
;                 f32x4 kd, ke;
;                 for (int j = 0; j < 4; ++j) { kd[j] = v[j] * __expf(-b4[j]); ke[j] = v[j] * __expf(bl[j] - b4[j]); }
;                 tile_put4(rl, pcl, pk4(kd));
.LBB0_1879:
	s_cmp_lt_i32 s37, 2
	s_cbranch_scc1 .LBB0_1889
	s_cmp_lg_u32 s37, 2
	s_cbranch_scc0 .LBB0_1886
	s_sub_i32 s20, s7, s36
	s_waitcnt vmcnt(0)
	v_add_u32_e32 v128, s20, v149
	v_readlane_b32 s20, v253, 54
	v_readlane_b32 s21, v253, 55
	v_ashrrev_i32_e32 v129, 31, v128
	s_andn2_b64 vcc, exec, s[16:17]
	v_lshl_add_u64 v[130:131], s[20:21], 0, v[136:137]
	v_lshl_add_u64 v[128:129], v[128:129], 2, v[130:131]
	s_waitcnt vmcnt(0)
	v_mov_b32_e32 v128, v192
	v_mov_b32_e32 v129, v193
	v_mov_b32_e32 v130, v194
	v_mov_b32_e32 v131, v195
	v_or_b32_e32 v136, v141, v147
	v_lshrrev_b32_e32 v136, 3, v136
	s_mov_b64 s[20:21], -1
	v_xor_b32_e32 v136, v136, v201
	s_cbranch_vccnz .LBB0_1883
	s_waitcnt vmcnt(0)
	v_mul_f32_e32 v137, 0xbfb8aa3b, v128
	v_exp_f32_e32 v160, v137
	v_mul_f32_e32 v137, 0xbfb8aa3b, v129
	v_exp_f32_e32 v161, v137
	v_mul_f32_e32 v137, 0xbfb8aa3b, v130
	v_exp_f32_e32 v162, v137
	v_mul_f32_e32 v137, 0xbfb8aa3b, v131
	v_exp_f32_e32 v163, v137
	v_pk_mul_f32 v[160:161], v[48:49], v[160:161]
	v_lshlrev_b32_e32 v137, 4, v136
	v_cvt_pk_bf16_f32 v160, v160, v161
	v_pk_mul_f32 v[162:163], v[50:51], v[162:163]
	s_mov_b64 s[20:21], 0
	v_cvt_pk_bf16_f32 v161, v162, v163
	v_lshlrev_b32_e32 v162, 3, v140
	v_add3_u32 v137, v159, v137, v162
	ds_write_b64 v137, v[160:161]

; DEV u32x2 pk4(f32x4 v) { u32x2 r = {pk_bf16(v[0], v[1]), pk_bf16(v[2], v[3])}; return r; }
; DEV int sig4(int x) { return ((x & 1) << 1) | (x >> 1); }
;   DEV void operator()(f32x4 (&acc)[2][2][4][2], int brow, int bcol, int wr, int wc, int fr, int fq) const {
;     ...
;               const f32x4 b4 = *(const f32x4*)(bmat + (size_t)tok * 1024 + lc);
;               const int pcl = (cl & ~15) + 4 * sig4((cl >> 2) & 3);
;               if (mode == 3) {
;                 for (int j = 0; j < 4; ++j) v[j] = v[j] * scale * __expf(b4[j]);
;                 tile_put4(rl, pcl, pk4(v));
;               } else {
;                 const f32x4 bl = *(const f32x4*)(bmat + (size_t)(tok | 63) * 1024 + lc);
;                 f32x4 kd, ke;
;                 for (int j = 0; j < 4; ++j) { kd[j] = v[j] * __expf(-b4[j]); ke[j] = v[j] * __expf(bl[j] - b4[j]); }
;                 tile_put4(rl, pcl, pk4(kd));
.LBB0_1900:
	s_waitcnt vmcnt(0)
	v_add_u32_e32 v129, 0x90, v144
	v_add_u32_e32 v128, s5, v129
	v_lshl_add_u32 v159, v129, 9, 0
	v_ashrrev_i32_e32 v129, 31, v128
	v_lshlrev_b64 v[136:137], 12, v[128:129]
	s_cmp_lt_i32 s37, 1
	s_mov_b64 s[20:21], -1
	s_cbranch_scc1 .LBB0_1956
	s_cmp_lt_i32 s37, 2
	s_cbranch_scc1 .LBB0_1911
	s_cmp_lg_u32 s37, 2
	s_cbranch_scc0 .LBB0_1908
	v_add_u32_e32 v128, s7, v203
	v_readlane_b32 s20, v253, 54
	v_subrev_u32_e32 v128, s36, v128
	v_readlane_b32 s21, v253, 55
	v_ashrrev_i32_e32 v129, 31, v128
	v_or_b32_e32 v160, v141, v142
	v_lshl_add_u64 v[130:131], s[20:21], 0, v[136:137]
	v_lshl_add_u64 v[128:129], v[128:129], 2, v[130:131]
	s_waitcnt vmcnt(0)
	v_mov_b32_e32 v128, v206
	v_mov_b32_e32 v129, v207
	v_mov_b32_e32 v130, v208
	v_mov_b32_e32 v131, v209
	v_lshrrev_b32_e32 v160, 3, v160
	s_mov_b64 s[20:21], -1
	s_andn2_b64 vcc, exec, s[16:17]
	v_xor_b32_e32 v160, v160, v150
	s_cbranch_vccnz .LBB0_1905
	s_waitcnt vmcnt(0)
	v_mul_f32_e32 v161, 0xbfb8aa3b, v128
	v_exp_f32_e32 v162, v161
	v_mul_f32_e32 v161, 0xbfb8aa3b, v129
	v_exp_f32_e32 v163, v161
	v_mul_f32_e32 v161, 0xbfb8aa3b, v130
	v_exp_f32_e32 v164, v161
	v_mul_f32_e32 v161, 0xbfb8aa3b, v131
	v_exp_f32_e32 v165, v161
	v_pk_mul_f32 v[162:163], v[44:45], v[162:163]
	v_lshlrev_b32_e32 v161, 4, v160
	v_cvt_pk_bf16_f32 v162, v162, v163
	v_pk_mul_f32 v[164:165], v[46:47], v[164:165]
	s_mov_b64 s[20:21], 0
	v_cvt_pk_bf16_f32 v163, v164, v165
	v_lshlrev_b32_e32 v164, 3, v140
	v_add3_u32 v161, v159, v161, v164
	ds_write_b64 v161, v[162:163]

; DEV u32x2 pk4(f32x4 v) { u32x2 r = {pk_bf16(v[0], v[1]), pk_bf16(v[2], v[3])}; return r; }
; DEV int sig4(int x) { return ((x & 1) << 1) | (x >> 1); }
;   DEV void operator()(f32x4 (&acc)[2][2][4][2], int brow, int bcol, int wr, int wc, int fr, int fq) const {
;     ...
;               const f32x4 b4 = *(const f32x4*)(bmat + (size_t)tok * 1024 + lc);
;               const int pcl = (cl & ~15) + 4 * sig4((cl >> 2) & 3);
;               if (mode == 3) {
;                 for (int j = 0; j < 4; ++j) v[j] = v[j] * scale * __expf(b4[j]);
;                 tile_put4(rl, pcl, pk4(v));
;               } else {
;                 const f32x4 bl = *(const f32x4*)(bmat + (size_t)(tok | 63) * 1024 + lc);
;                 f32x4 kd, ke;
;                 for (int j = 0; j < 4; ++j) { kd[j] = v[j] * __expf(-b4[j]); ke[j] = v[j] * __expf(bl[j] - b4[j]); }
;                 tile_put4(rl, pcl, pk4(kd));
.LBB0_1915:
	s_cmp_lt_i32 s37, 2
	s_cbranch_scc1 .LBB0_1925
	s_cmp_lg_u32 s37, 2
	s_cbranch_scc0 .LBB0_1922
	s_sub_i32 s20, s7, s36
	s_waitcnt vmcnt(0)
	v_add_u32_e32 v128, s20, v146
	v_readlane_b32 s20, v253, 54
	v_readlane_b32 s21, v253, 55
	v_ashrrev_i32_e32 v129, 31, v128
	v_or_b32_e32 v160, v141, v143
	v_lshl_add_u64 v[130:131], s[20:21], 0, v[136:137]
	v_lshl_add_u64 v[128:129], v[128:129], 2, v[130:131]
	s_waitcnt vmcnt(0)
	v_mov_b32_e32 v128, v210
	v_mov_b32_e32 v129, v211
	v_mov_b32_e32 v130, v212
	v_mov_b32_e32 v131, v213
	v_lshrrev_b32_e32 v160, 3, v160
	s_mov_b64 s[20:21], -1
	s_andn2_b64 vcc, exec, s[16:17]
	v_xor_b32_e32 v160, v160, v150
	s_cbranch_vccnz .LBB0_1919
	s_waitcnt vmcnt(0)
	v_mul_f32_e32 v161, 0xbfb8aa3b, v128
	v_exp_f32_e32 v162, v161
	v_mul_f32_e32 v161, 0xbfb8aa3b, v129
	v_exp_f32_e32 v163, v161
	v_mul_f32_e32 v161, 0xbfb8aa3b, v130
	v_exp_f32_e32 v164, v161
	v_mul_f32_e32 v161, 0xbfb8aa3b, v131
	v_exp_f32_e32 v165, v161
	v_pk_mul_f32 v[162:163], v[40:41], v[162:163]
	v_lshlrev_b32_e32 v161, 4, v160
	v_cvt_pk_bf16_f32 v162, v162, v163
	v_pk_mul_f32 v[164:165], v[42:43], v[164:165]
	s_mov_b64 s[20:21], 0
	v_cvt_pk_bf16_f32 v163, v164, v165
	v_lshlrev_b32_e32 v164, 3, v140
	v_add3_u32 v161, v159, v161, v164
	ds_write_b64 v161, v[162:163]

; DEV u32x2 pk4(f32x4 v) { u32x2 r = {pk_bf16(v[0], v[1]), pk_bf16(v[2], v[3])}; return r; }
; DEV int sig4(int x) { return ((x & 1) << 1) | (x >> 1); }
;   DEV void operator()(f32x4 (&acc)[2][2][4][2], int brow, int bcol, int wr, int wc, int fr, int fq) const {
;     ...
;               const f32x4 b4 = *(const f32x4*)(bmat + (size_t)tok * 1024 + lc);
;               const int pcl = (cl & ~15) + 4 * sig4((cl >> 2) & 3);
;               if (mode == 3) {
;                 for (int j = 0; j < 4; ++j) v[j] = v[j] * scale * __expf(b4[j]);
;                 tile_put4(rl, pcl, pk4(v));
;               } else {
;                 const f32x4 bl = *(const f32x4*)(bmat + (size_t)(tok | 63) * 1024 + lc);
;                 f32x4 kd, ke;
;                 for (int j = 0; j < 4; ++j) { kd[j] = v[j] * __expf(-b4[j]); ke[j] = v[j] * __expf(bl[j] - b4[j]); }
;                 tile_put4(rl, pcl, pk4(kd));
.LBB0_1929:
	s_cmp_lt_i32 s37, 2
	s_cbranch_scc1 .LBB0_1939
	s_cmp_lg_u32 s37, 2
	s_cbranch_scc0 .LBB0_1936
	s_sub_i32 s20, s7, s36
	s_waitcnt vmcnt(0)
	v_add_u32_e32 v128, s20, v148
	v_readlane_b32 s20, v253, 54
	v_readlane_b32 s21, v253, 55
	v_ashrrev_i32_e32 v129, 31, v128
	v_or_b32_e32 v160, v141, v145
	v_lshl_add_u64 v[130:131], s[20:21], 0, v[136:137]
	v_lshl_add_u64 v[128:129], v[128:129], 2, v[130:131]
	s_waitcnt vmcnt(0)
	v_mov_b32_e32 v128, v214
	v_mov_b32_e32 v129, v215
	v_mov_b32_e32 v130, v216
	v_mov_b32_e32 v131, v217
	v_lshrrev_b32_e32 v160, 3, v160
	s_mov_b64 s[20:21], -1
	s_andn2_b64 vcc, exec, s[16:17]
	v_xor_b32_e32 v160, v160, v150
	s_cbranch_vccnz .LBB0_1933
	s_waitcnt vmcnt(0)
	v_mul_f32_e32 v161, 0xbfb8aa3b, v128
	v_exp_f32_e32 v162, v161
	v_mul_f32_e32 v161, 0xbfb8aa3b, v129
	v_exp_f32_e32 v163, v161
	v_mul_f32_e32 v161, 0xbfb8aa3b, v130
	v_exp_f32_e32 v164, v161
	v_mul_f32_e32 v161, 0xbfb8aa3b, v131
	v_exp_f32_e32 v165, v161
	v_pk_mul_f32 v[162:163], v[36:37], v[162:163]
	v_lshlrev_b32_e32 v161, 4, v160
	v_cvt_pk_bf16_f32 v162, v162, v163
	v_pk_mul_f32 v[164:165], v[38:39], v[164:165]
	s_mov_b64 s[20:21], 0
	v_cvt_pk_bf16_f32 v163, v164, v165
	v_lshlrev_b32_e32 v164, 3, v140
	v_add3_u32 v161, v159, v161, v164
	ds_write_b64 v161, v[162:163]

; DEV u32x2 pk4(f32x4 v) { u32x2 r = {pk_bf16(v[0], v[1]), pk_bf16(v[2], v[3])}; return r; }
; DEV int sig4(int x) { return ((x & 1) << 1) | (x >> 1); }
;   DEV void operator()(f32x4 (&acc)[2][2][4][2], int brow, int bcol, int wr, int wc, int fr, int fq) const {
;     ...
;               const f32x4 b4 = *(const f32x4*)(bmat + (size_t)tok * 1024 + lc);
;               const int pcl = (cl & ~15) + 4 * sig4((cl >> 2) & 3);
;               if (mode == 3) {
;                 for (int j = 0; j < 4; ++j) v[j] = v[j] * scale * __expf(b4[j]);
;                 tile_put4(rl, pcl, pk4(v));
;               } else {
;                 const f32x4 bl = *(const f32x4*)(bmat + (size_t)(tok | 63) * 1024 + lc);
;                 f32x4 kd, ke;
;                 for (int j = 0; j < 4; ++j) { kd[j] = v[j] * __expf(-b4[j]); ke[j] = v[j] * __expf(bl[j] - b4[j]); }
;                 tile_put4(rl, pcl, pk4(kd));
.LBB0_1943:
	s_cmp_lt_i32 s37, 2
	s_cbranch_scc1 .LBB0_1953
	s_cmp_lg_u32 s37, 2
	s_cbranch_scc0 .LBB0_1950
	s_sub_i32 s20, s7, s36
	s_waitcnt vmcnt(0)
	v_add_u32_e32 v128, s20, v149
	v_readlane_b32 s20, v253, 54
	v_readlane_b32 s21, v253, 55
	v_ashrrev_i32_e32 v129, 31, v128
	s_andn2_b64 vcc, exec, s[16:17]
	v_lshl_add_u64 v[130:131], s[20:21], 0, v[136:137]
	v_lshl_add_u64 v[128:129], v[128:129], 2, v[130:131]
	s_waitcnt vmcnt(0)
	v_mov_b32_e32 v128, v224
	v_mov_b32_e32 v129, v225
	v_mov_b32_e32 v130, v226
	v_mov_b32_e32 v131, v227
	v_or_b32_e32 v136, v141, v147
	v_lshrrev_b32_e32 v136, 3, v136
	s_mov_b64 s[20:21], -1
	v_xor_b32_e32 v136, v136, v150
	s_cbranch_vccnz .LBB0_1947
	s_waitcnt vmcnt(0)
	v_mul_f32_e32 v137, 0xbfb8aa3b, v128
	v_exp_f32_e32 v160, v137
	v_mul_f32_e32 v137, 0xbfb8aa3b, v129
	v_exp_f32_e32 v161, v137
	v_mul_f32_e32 v137, 0xbfb8aa3b, v130
	v_exp_f32_e32 v162, v137
	v_mul_f32_e32 v137, 0xbfb8aa3b, v131
	v_exp_f32_e32 v163, v137
	v_pk_mul_f32 v[160:161], v[32:33], v[160:161]
	v_lshlrev_b32_e32 v137, 4, v136
	v_cvt_pk_bf16_f32 v160, v160, v161
	v_pk_mul_f32 v[162:163], v[34:35], v[162:163]
	s_mov_b64 s[20:21], 0
	v_cvt_pk_bf16_f32 v161, v162, v163
	v_lshlrev_b32_e32 v162, 3, v140
	v_add3_u32 v137, v159, v137, v162
	ds_write_b64 v137, v[160:161]

; DEV u32x2 pk4(f32x4 v) { u32x2 r = {pk_bf16(v[0], v[1]), pk_bf16(v[2], v[3])}; return r; }
; DEV int sig4(int x) { return ((x & 1) << 1) | (x >> 1); }
;   DEV void operator()(f32x4 (&acc)[2][2][4][2], int brow, int bcol, int wr, int wc, int fr, int fq) const {
;     ...
;               const f32x4 b4 = *(const f32x4*)(bmat + (size_t)tok * 1024 + lc);
;               const int pcl = (cl & ~15) + 4 * sig4((cl >> 2) & 3);
;               if (mode == 3) {
;                 for (int j = 0; j < 4; ++j) v[j] = v[j] * scale * __expf(b4[j]);
;                 tile_put4(rl, pcl, pk4(v));
;               } else {
;                 const f32x4 bl = *(const f32x4*)(bmat + (size_t)(tok | 63) * 1024 + lc);
;                 f32x4 kd, ke;
;                 for (int j = 0; j < 4; ++j) { kd[j] = v[j] * __expf(-b4[j]); ke[j] = v[j] * __expf(bl[j] - b4[j]); }
;                 tile_put4(rl, pcl, pk4(kd));
.LBB0_1964:
	s_waitcnt vmcnt(0)
	v_add_u32_e32 v129, 0xa0, v144
	v_add_u32_e32 v128, s5, v129
	v_lshl_add_u32 v159, v129, 9, 0
	v_ashrrev_i32_e32 v129, 31, v128
	v_lshlrev_b64 v[136:137], 12, v[128:129]
	s_cmp_lt_i32 s37, 1
	s_mov_b64 s[20:21], -1
	s_cbranch_scc1 .LBB0_2020
	s_cmp_lt_i32 s37, 2
	s_cbranch_scc1 .LBB0_1975
	s_cmp_lg_u32 s37, 2
	s_cbranch_scc0 .LBB0_1972
	v_add_u32_e32 v128, s7, v203
	v_readlane_b32 s20, v253, 54
	v_subrev_u32_e32 v128, s36, v128
	v_readlane_b32 s21, v253, 55
	v_ashrrev_i32_e32 v129, 31, v128
	v_or_b32_e32 v160, v141, v142
	v_lshl_add_u64 v[130:131], s[20:21], 0, v[136:137]
	v_lshl_add_u64 v[128:129], v[128:129], 2, v[130:131]
	s_waitcnt vmcnt(0)
	v_mov_b32_e32 v128, v228
	v_mov_b32_e32 v129, v229
	v_mov_b32_e32 v130, v230
	v_mov_b32_e32 v131, v231
	v_lshrrev_b32_e32 v160, 3, v160
	s_mov_b64 s[20:21], -1
	s_andn2_b64 vcc, exec, s[16:17]
	v_xor_b32_e32 v160, v160, v201
	s_cbranch_vccnz .LBB0_1969
	s_waitcnt vmcnt(0)
	v_mul_f32_e32 v161, 0xbfb8aa3b, v128
	v_exp_f32_e32 v162, v161
	v_mul_f32_e32 v161, 0xbfb8aa3b, v129
	v_exp_f32_e32 v163, v161
	v_mul_f32_e32 v161, 0xbfb8aa3b, v130
	v_exp_f32_e32 v164, v161
	v_mul_f32_e32 v161, 0xbfb8aa3b, v131
	v_exp_f32_e32 v165, v161
	v_pk_mul_f32 v[162:163], v[28:29], v[162:163]
	v_lshlrev_b32_e32 v161, 4, v160
	v_cvt_pk_bf16_f32 v162, v162, v163
	v_pk_mul_f32 v[164:165], v[30:31], v[164:165]
	s_mov_b64 s[20:21], 0
	v_cvt_pk_bf16_f32 v163, v164, v165
	v_lshlrev_b32_e32 v164, 3, v140
	v_add3_u32 v161, v159, v161, v164
	ds_write_b64 v161, v[162:163]

; DEV u32x2 pk4(f32x4 v) { u32x2 r = {pk_bf16(v[0], v[1]), pk_bf16(v[2], v[3])}; return r; }
; DEV int sig4(int x) { return ((x & 1) << 1) | (x >> 1); }
;   DEV void operator()(f32x4 (&acc)[2][2][4][2], int brow, int bcol, int wr, int wc, int fr, int fq) const {
;     ...
;               const f32x4 b4 = *(const f32x4*)(bmat + (size_t)tok * 1024 + lc);
;               const int pcl = (cl & ~15) + 4 * sig4((cl >> 2) & 3);
;               if (mode == 3) {
;                 for (int j = 0; j < 4; ++j) v[j] = v[j] * scale * __expf(b4[j]);
;                 tile_put4(rl, pcl, pk4(v));
;               } else {
;                 const f32x4 bl = *(const f32x4*)(bmat + (size_t)(tok | 63) * 1024 + lc);
;                 f32x4 kd, ke;
;                 for (int j = 0; j < 4; ++j) { kd[j] = v[j] * __expf(-b4[j]); ke[j] = v[j] * __expf(bl[j] - b4[j]); }
;                 tile_put4(rl, pcl, pk4(kd));
.LBB0_1979:
	s_cmp_lt_i32 s37, 2
	s_cbranch_scc1 .LBB0_1989
	s_cmp_lg_u32 s37, 2
	s_cbranch_scc0 .LBB0_1986
	s_sub_i32 s20, s7, s36
	s_waitcnt vmcnt(0)
	v_add_u32_e32 v128, s20, v146
	v_readlane_b32 s20, v253, 54
	v_readlane_b32 s21, v253, 55
	v_ashrrev_i32_e32 v129, 31, v128
	v_or_b32_e32 v151, v141, v143
	v_lshl_add_u64 v[130:131], s[20:21], 0, v[136:137]
	v_lshl_add_u64 v[128:129], v[128:129], 2, v[130:131]
	s_waitcnt vmcnt(0)
	v_mov_b32_e32 v128, v232
	v_mov_b32_e32 v129, v233
	v_mov_b32_e32 v130, v234
	v_mov_b32_e32 v131, v235
	v_lshrrev_b32_e32 v151, 3, v151
	s_mov_b64 s[20:21], -1
	s_andn2_b64 vcc, exec, s[16:17]
	v_xor_b32_e32 v151, v151, v201
	s_cbranch_vccnz .LBB0_1983
	s_waitcnt vmcnt(0)
	v_mul_f32_e32 v160, 0xbfb8aa3b, v128
	v_mul_f32_e32 v161, 0xbfb8aa3b, v129
	v_mul_f32_e32 v162, 0xbfb8aa3b, v130
	v_mul_f32_e32 v163, 0xbfb8aa3b, v131
	v_exp_f32_e32 v160, v160
	v_exp_f32_e32 v161, v161
	v_exp_f32_e32 v162, v162
	v_exp_f32_e32 v163, v163
	s_mov_b64 s[20:21], 0
	v_pk_mul_f32 v[160:161], v[24:25], v[160:161]
	v_pk_mul_f32 v[162:163], v[26:27], v[162:163]
	v_cvt_pk_bf16_f32 v160, v160, v161
	v_cvt_pk_bf16_f32 v161, v162, v163
	v_lshlrev_b32_e32 v162, 4, v151
	v_lshlrev_b32_e32 v163, 3, v140
	v_add3_u32 v162, v159, v162, v163
	ds_write_b64 v162, v[160:161]

; DEV u32x2 pk4(f32x4 v) { u32x2 r = {pk_bf16(v[0], v[1]), pk_bf16(v[2], v[3])}; return r; }
; DEV int sig4(int x) { return ((x & 1) << 1) | (x >> 1); }
;   DEV void operator()(f32x4 (&acc)[2][2][4][2], int brow, int bcol, int wr, int wc, int fr, int fq) const {
;     ...
;               const f32x4 b4 = *(const f32x4*)(bmat + (size_t)tok * 1024 + lc);
;               const int pcl = (cl & ~15) + 4 * sig4((cl >> 2) & 3);
;               if (mode == 3) {
;                 for (int j = 0; j < 4; ++j) v[j] = v[j] * scale * __expf(b4[j]);
;                 tile_put4(rl, pcl, pk4(v));
;               } else {
;                 const f32x4 bl = *(const f32x4*)(bmat + (size_t)(tok | 63) * 1024 + lc);
;                 f32x4 kd, ke;
;                 for (int j = 0; j < 4; ++j) { kd[j] = v[j] * __expf(-b4[j]); ke[j] = v[j] * __expf(bl[j] - b4[j]); }
;                 tile_put4(rl, pcl, pk4(kd));
.LBB0_1993:
	s_cmp_lt_i32 s37, 2
	s_cbranch_scc1 .LBB0_2003
	s_cmp_lg_u32 s37, 2
	s_cbranch_scc0 .LBB0_2000
	s_sub_i32 s20, s7, s36
	s_waitcnt vmcnt(0)
	v_add_u32_e32 v128, s20, v148
	v_readlane_b32 s20, v253, 54
	v_readlane_b32 s21, v253, 55
	v_ashrrev_i32_e32 v129, 31, v128
	v_or_b32_e32 v151, v141, v145
	v_lshl_add_u64 v[130:131], s[20:21], 0, v[136:137]
	v_lshl_add_u64 v[128:129], v[128:129], 2, v[130:131]
	s_waitcnt vmcnt(0)
	v_mov_b32_e32 v128, v236
	v_mov_b32_e32 v129, v237
	v_mov_b32_e32 v130, v238
	v_mov_b32_e32 v131, v239
	v_lshrrev_b32_e32 v151, 3, v151
	s_mov_b64 s[20:21], -1
	s_andn2_b64 vcc, exec, s[16:17]
	v_xor_b32_e32 v151, v151, v201
	s_cbranch_vccnz .LBB0_1997
	s_waitcnt vmcnt(0)
	v_mul_f32_e32 v152, 0xbfb8aa3b, v128
	v_exp_f32_e32 v160, v152
	v_mul_f32_e32 v152, 0xbfb8aa3b, v129
	v_exp_f32_e32 v161, v152
	v_mul_f32_e32 v152, 0xbfb8aa3b, v130
	v_exp_f32_e32 v162, v152
	v_mul_f32_e32 v152, 0xbfb8aa3b, v131
	v_exp_f32_e32 v163, v152
	v_pk_mul_f32 v[160:161], v[20:21], v[160:161]
	v_lshlrev_b32_e32 v152, 4, v151
	v_cvt_pk_bf16_f32 v160, v160, v161
	v_pk_mul_f32 v[162:163], v[22:23], v[162:163]
	s_mov_b64 s[20:21], 0
	v_cvt_pk_bf16_f32 v161, v162, v163
	v_lshlrev_b32_e32 v162, 3, v140
	v_add3_u32 v152, v159, v152, v162
	ds_write_b64 v152, v[160:161]

; DEV u32x2 pk4(f32x4 v) { u32x2 r = {pk_bf16(v[0], v[1]), pk_bf16(v[2], v[3])}; return r; }
; DEV int sig4(int x) { return ((x & 1) << 1) | (x >> 1); }
;   DEV void operator()(f32x4 (&acc)[2][2][4][2], int brow, int bcol, int wr, int wc, int fr, int fq) const {
;     ...
;               const f32x4 b4 = *(const f32x4*)(bmat + (size_t)tok * 1024 + lc);
;               const int pcl = (cl & ~15) + 4 * sig4((cl >> 2) & 3);
;               if (mode == 3) {
;                 for (int j = 0; j < 4; ++j) v[j] = v[j] * scale * __expf(b4[j]);
;                 tile_put4(rl, pcl, pk4(v));
;               } else {
;                 const f32x4 bl = *(const f32x4*)(bmat + (size_t)(tok | 63) * 1024 + lc);
;                 f32x4 kd, ke;
;                 for (int j = 0; j < 4; ++j) { kd[j] = v[j] * __expf(-b4[j]); ke[j] = v[j] * __expf(bl[j] - b4[j]); }
;                 tile_put4(rl, pcl, pk4(kd));
.LBB0_2007:
	s_cmp_lt_i32 s37, 2
	s_cbranch_scc1 .LBB0_2017
	s_cmp_lg_u32 s37, 2
	s_cbranch_scc0 .LBB0_2014
	s_sub_i32 s20, s7, s36
	s_waitcnt vmcnt(0)
	v_add_u32_e32 v128, s20, v149
	v_readlane_b32 s20, v253, 54
	v_readlane_b32 s21, v253, 55
	v_ashrrev_i32_e32 v129, 31, v128
	s_andn2_b64 vcc, exec, s[16:17]
	v_lshl_add_u64 v[130:131], s[20:21], 0, v[136:137]
	v_lshl_add_u64 v[128:129], v[128:129], 2, v[130:131]
	s_waitcnt vmcnt(0)
	v_mov_b32_e32 v128, v240
	v_mov_b32_e32 v129, v241
	v_mov_b32_e32 v130, v242
	v_mov_b32_e32 v131, v243
	v_or_b32_e32 v136, v141, v147
	v_lshrrev_b32_e32 v136, 3, v136
	s_mov_b64 s[20:21], -1
	v_xor_b32_e32 v136, v136, v201
	s_cbranch_vccnz .LBB0_2011
	s_waitcnt vmcnt(0)
	v_mul_f32_e32 v137, 0xbfb8aa3b, v128
	v_exp_f32_e32 v152, v137
	v_mul_f32_e32 v137, 0xbfb8aa3b, v129
	v_exp_f32_e32 v153, v137
	v_mul_f32_e32 v137, 0xbfb8aa3b, v130
	v_exp_f32_e32 v160, v137
	v_mul_f32_e32 v137, 0xbfb8aa3b, v131
	v_exp_f32_e32 v161, v137
	v_pk_mul_f32 v[152:153], v[16:17], v[152:153]
	v_lshlrev_b32_e32 v137, 4, v136
	v_lshlrev_b32_e32 v151, 3, v140
	v_pk_mul_f32 v[160:161], v[18:19], v[160:161]
	v_cvt_pk_bf16_f32 v152, v152, v153
	v_cvt_pk_bf16_f32 v153, v160, v161
	v_add3_u32 v137, v159, v137, v151
	s_mov_b64 s[20:21], 0
	ds_write_b64 v137, v[152:153]

; DEV u32x2 pk4(f32x4 v) { u32x2 r = {pk_bf16(v[0], v[1]), pk_bf16(v[2], v[3])}; return r; }
; DEV int sig4(int x) { return ((x & 1) << 1) | (x >> 1); }
;   DEV void operator()(f32x4 (&acc)[2][2][4][2], int brow, int bcol, int wr, int wc, int fr, int fq) const {
;     ...
;               const f32x4 b4 = *(const f32x4*)(bmat + (size_t)tok * 1024 + lc);
;               const int pcl = (cl & ~15) + 4 * sig4((cl >> 2) & 3);
;               if (mode == 3) {
;                 for (int j = 0; j < 4; ++j) v[j] = v[j] * scale * __expf(b4[j]);
;                 tile_put4(rl, pcl, pk4(v));
;               } else {
;                 const f32x4 bl = *(const f32x4*)(bmat + (size_t)(tok | 63) * 1024 + lc);
;                 f32x4 kd, ke;
;                 for (int j = 0; j < 4; ++j) { kd[j] = v[j] * __expf(-b4[j]); ke[j] = v[j] * __expf(bl[j] - b4[j]); }
;                 tile_put4(rl, pcl, pk4(kd));
.LBB0_2028:
	s_waitcnt vmcnt(0)
	v_add_u32_e32 v129, 0xb0, v144
	v_add_u32_e32 v128, s5, v129
	v_lshl_add_u32 v144, v129, 9, 0
	v_ashrrev_i32_e32 v129, 31, v128
	v_lshlrev_b64 v[136:137], 12, v[128:129]
	s_cmp_lt_i32 s37, 1
	s_mov_b64 s[20:21], -1
	s_cbranch_scc1 .LBB0_2084
	s_cmp_lt_i32 s37, 2
	s_cbranch_scc1 .LBB0_2039
	s_cmp_lg_u32 s37, 2
	s_cbranch_scc0 .LBB0_2036
	v_add_u32_e32 v128, s7, v203
	v_readlane_b32 s20, v253, 54
	v_subrev_u32_e32 v128, s36, v128
	v_readlane_b32 s21, v253, 55
	v_ashrrev_i32_e32 v129, 31, v128
	v_or_b32_e32 v142, v141, v142
	v_lshl_add_u64 v[130:131], s[20:21], 0, v[136:137]
	v_lshl_add_u64 v[128:129], v[128:129], 2, v[130:131]
	s_waitcnt vmcnt(0)
	v_mov_b32_e32 v128, v244
	v_mov_b32_e32 v129, v245
	v_mov_b32_e32 v130, v246
	v_mov_b32_e32 v131, v247
	v_lshrrev_b32_e32 v142, 3, v142
	s_mov_b64 s[20:21], -1
	s_andn2_b64 vcc, exec, s[16:17]
	v_xor_b32_e32 v142, v142, v150
	s_cbranch_vccnz .LBB0_2033
	s_waitcnt vmcnt(0)
	v_mul_f32_e32 v151, 0xbfb8aa3b, v128
	v_exp_f32_e32 v152, v151
	v_mul_f32_e32 v151, 0xbfb8aa3b, v129
	v_exp_f32_e32 v153, v151
	v_mul_f32_e32 v151, 0xbfb8aa3b, v130
	v_exp_f32_e32 v160, v151
	v_mul_f32_e32 v151, 0xbfb8aa3b, v131
	v_exp_f32_e32 v161, v151
	v_pk_mul_f32 v[152:153], v[12:13], v[152:153]
	v_lshlrev_b32_e32 v151, 4, v142
	v_lshlrev_b32_e32 v154, 3, v140
	v_pk_mul_f32 v[160:161], v[14:15], v[160:161]
	v_cvt_pk_bf16_f32 v152, v152, v153
	v_cvt_pk_bf16_f32 v153, v160, v161
	v_add3_u32 v151, v144, v151, v154
	s_mov_b64 s[20:21], 0
	ds_write_b64 v151, v[152:153]

; DEV u32x2 pk4(f32x4 v) { u32x2 r = {pk_bf16(v[0], v[1]), pk_bf16(v[2], v[3])}; return r; }
; DEV int sig4(int x) { return ((x & 1) << 1) | (x >> 1); }
;   DEV void operator()(f32x4 (&acc)[2][2][4][2], int brow, int bcol, int wr, int wc, int fr, int fq) const {
;     ...
;               const f32x4 b4 = *(const f32x4*)(bmat + (size_t)tok * 1024 + lc);
;               const int pcl = (cl & ~15) + 4 * sig4((cl >> 2) & 3);
;               if (mode == 3) {
;                 for (int j = 0; j < 4; ++j) v[j] = v[j] * scale * __expf(b4[j]);
;                 tile_put4(rl, pcl, pk4(v));
;               } else {
;                 const f32x4 bl = *(const f32x4*)(bmat + (size_t)(tok | 63) * 1024 + lc);
;                 f32x4 kd, ke;
;                 for (int j = 0; j < 4; ++j) { kd[j] = v[j] * __expf(-b4[j]); ke[j] = v[j] * __expf(bl[j] - b4[j]); }
;                 tile_put4(rl, pcl, pk4(kd));
.LBB0_2043:
	s_cmp_lt_i32 s37, 2
	s_cbranch_scc1 .LBB0_2053
	s_cmp_lg_u32 s37, 2
	s_cbranch_scc0 .LBB0_2050
	s_sub_i32 s20, s7, s36
	s_waitcnt vmcnt(0)
	v_add_u32_e32 v128, s20, v146
	v_readlane_b32 s20, v253, 54
	v_readlane_b32 s21, v253, 55
	v_ashrrev_i32_e32 v129, 31, v128
	v_or_b32_e32 v142, v141, v143
	v_lshl_add_u64 v[130:131], s[20:21], 0, v[136:137]
	v_lshl_add_u64 v[128:129], v[128:129], 2, v[130:131]
	s_waitcnt vmcnt(0)
	v_mov_b32_e32 v128, v248
	v_mov_b32_e32 v129, v249
	v_mov_b32_e32 v130, v250
	v_mov_b32_e32 v131, v251
	v_lshrrev_b32_e32 v142, 3, v142
	s_mov_b64 s[20:21], -1
	s_andn2_b64 vcc, exec, s[16:17]
	v_xor_b32_e32 v142, v142, v150
	s_cbranch_vccnz .LBB0_2047
	s_waitcnt vmcnt(0)
	v_mul_f32_e32 v143, 0xbfb8aa3b, v128
	v_exp_f32_e32 v152, v143
	v_mul_f32_e32 v143, 0xbfb8aa3b, v129
	v_exp_f32_e32 v153, v143
	v_mul_f32_e32 v143, 0xbfb8aa3b, v130
	v_exp_f32_e32 v154, v143
	v_mul_f32_e32 v143, 0xbfb8aa3b, v131
	v_exp_f32_e32 v155, v143
	v_pk_mul_f32 v[152:153], v[8:9], v[152:153]
	v_lshlrev_b32_e32 v143, 4, v142
	v_lshlrev_b32_e32 v146, 3, v140
	v_pk_mul_f32 v[154:155], v[10:11], v[154:155]
	v_cvt_pk_bf16_f32 v152, v152, v153
	v_cvt_pk_bf16_f32 v153, v154, v155
	v_add3_u32 v143, v144, v143, v146
	s_mov_b64 s[20:21], 0
	ds_write_b64 v143, v[152:153]

; DEV u32x2 pk4(f32x4 v) { u32x2 r = {pk_bf16(v[0], v[1]), pk_bf16(v[2], v[3])}; return r; }
; DEV int sig4(int x) { return ((x & 1) << 1) | (x >> 1); }
;   DEV void operator()(f32x4 (&acc)[2][2][4][2], int brow, int bcol, int wr, int wc, int fr, int fq) const {
;     ...
;               const f32x4 b4 = *(const f32x4*)(bmat + (size_t)tok * 1024 + lc);
;               const int pcl = (cl & ~15) + 4 * sig4((cl >> 2) & 3);
;               if (mode == 3) {
;                 for (int j = 0; j < 4; ++j) v[j] = v[j] * scale * __expf(b4[j]);
;                 tile_put4(rl, pcl, pk4(v));
;               } else {
;                 const f32x4 bl = *(const f32x4*)(bmat + (size_t)(tok | 63) * 1024 + lc);
;                 f32x4 kd, ke;
;                 for (int j = 0; j < 4; ++j) { kd[j] = v[j] * __expf(-b4[j]); ke[j] = v[j] * __expf(bl[j] - b4[j]); }
;                 tile_put4(rl, pcl, pk4(kd));
.LBB0_2057:
	s_cmp_lt_i32 s37, 2
	s_cbranch_scc1 .LBB0_2067
	s_cmp_lg_u32 s37, 2
	s_cbranch_scc0 .LBB0_2064
	s_sub_i32 s20, s7, s36
	s_waitcnt vmcnt(0)
	v_add_u32_e32 v128, s20, v148
	v_readlane_b32 s20, v253, 54
	v_readlane_b32 s21, v253, 55
	v_ashrrev_i32_e32 v129, 31, v128
	v_or_b32_e32 v142, v141, v145
	v_lshl_add_u64 v[130:131], s[20:21], 0, v[136:137]
	v_lshl_add_u64 v[128:129], v[128:129], 2, v[130:131]
	s_waitcnt vmcnt(0)
	v_mov_b32_e32 v128, v166
	v_mov_b32_e32 v129, v167
	v_mov_b32_e32 v130, v168
	v_mov_b32_e32 v131, v169
	v_lshrrev_b32_e32 v142, 3, v142
	s_mov_b64 s[20:21], -1
	s_andn2_b64 vcc, exec, s[16:17]
	v_xor_b32_e32 v142, v142, v150
	s_cbranch_vccnz .LBB0_2061
	s_waitcnt vmcnt(0)
	v_mul_f32_e32 v143, 0xbfb8aa3b, v128
	v_exp_f32_e32 v152, v143
	v_mul_f32_e32 v143, 0xbfb8aa3b, v129
	v_exp_f32_e32 v153, v143
	v_mul_f32_e32 v143, 0xbfb8aa3b, v130
	v_exp_f32_e32 v154, v143
	v_mul_f32_e32 v143, 0xbfb8aa3b, v131
	v_exp_f32_e32 v155, v143
	v_pk_mul_f32 v[152:153], v[4:5], v[152:153]
	v_lshlrev_b32_e32 v143, 4, v142
	v_lshlrev_b32_e32 v145, 3, v140
	v_pk_mul_f32 v[154:155], v[6:7], v[154:155]
	v_cvt_pk_bf16_f32 v152, v152, v153
	v_cvt_pk_bf16_f32 v153, v154, v155
	v_add3_u32 v143, v144, v143, v145
	s_mov_b64 s[20:21], 0
	ds_write_b64 v143, v[152:153]

; DEV u32x2 pk4(f32x4 v) { u32x2 r = {pk_bf16(v[0], v[1]), pk_bf16(v[2], v[3])}; return r; }
; DEV int sig4(int x) { return ((x & 1) << 1) | (x >> 1); }
;   DEV void operator()(f32x4 (&acc)[2][2][4][2], int brow, int bcol, int wr, int wc, int fr, int fq) const {
;     ...
;               const f32x4 b4 = *(const f32x4*)(bmat + (size_t)tok * 1024 + lc);
;               const int pcl = (cl & ~15) + 4 * sig4((cl >> 2) & 3);
;               if (mode == 3) {
;                 for (int j = 0; j < 4; ++j) v[j] = v[j] * scale * __expf(b4[j]);
;                 tile_put4(rl, pcl, pk4(v));
;               } else {
;                 const f32x4 bl = *(const f32x4*)(bmat + (size_t)(tok | 63) * 1024 + lc);
;                 f32x4 kd, ke;
;                 for (int j = 0; j < 4; ++j) { kd[j] = v[j] * __expf(-b4[j]); ke[j] = v[j] * __expf(bl[j] - b4[j]); }
;                 tile_put4(rl, pcl, pk4(kd));
.LBB0_2071:
	s_cmp_lt_i32 s37, 2
	s_cbranch_scc1 .LBB0_2081
	s_cmp_lg_u32 s37, 2
	s_cbranch_scc0 .LBB0_2078
	s_sub_i32 s20, s7, s36
	s_waitcnt vmcnt(0)
	v_add_u32_e32 v128, s20, v149
	v_readlane_b32 s20, v253, 54
	v_readlane_b32 s21, v253, 55
	v_ashrrev_i32_e32 v129, 31, v128
	s_andn2_b64 vcc, exec, s[16:17]
	v_lshl_add_u64 v[130:131], s[20:21], 0, v[136:137]
	v_lshl_add_u64 v[128:129], v[128:129], 2, v[130:131]
	s_waitcnt vmcnt(0)
	v_mov_b32_e32 v128, v170
	v_mov_b32_e32 v129, v171
	v_mov_b32_e32 v130, v172
	v_mov_b32_e32 v131, v173
	v_or_b32_e32 v136, v141, v147
	v_lshrrev_b32_e32 v137, 3, v136
	s_mov_b64 s[20:21], -1
	v_lshlrev_b32_e32 v136, 3, v140
	v_xor_b32_e32 v137, v137, v150
	s_cbranch_vccnz .LBB0_2075
	s_waitcnt vmcnt(0)
	v_mul_f32_e32 v140, 0xbfb8aa3b, v128
	v_mul_f32_e32 v141, 0xbfb8aa3b, v129
	v_mul_f32_e32 v142, 0xbfb8aa3b, v130
	v_mul_f32_e32 v143, 0xbfb8aa3b, v131
	v_exp_f32_e32 v140, v140
	v_exp_f32_e32 v141, v141
	v_exp_f32_e32 v142, v142
	v_exp_f32_e32 v143, v143
	s_mov_b64 s[20:21], 0
	v_pk_mul_f32 v[140:141], v[0:1], v[140:141]
	v_pk_mul_f32 v[142:143], v[2:3], v[142:143]
	v_cvt_pk_bf16_f32 v140, v140, v141
	v_cvt_pk_bf16_f32 v141, v142, v143
	v_lshlrev_b32_e32 v142, 4, v137
	v_add3_u32 v142, v144, v142, v136
	ds_write_b64 v142, v[140:141]
